# WKV scan: the 16 steps of a chunk fully unrolled (no inner loop counter/branches, immediate operand offsets)
# speedup vs baseline: 1.0038x; 1.0038x over previous
; __device__ __forceinline__ float red4(float x) { x += dppf(x, 0); x += dppf(x, 1); return x; }
; __device__ __forceinline__ void scan_phase(const Params& p, int j, unsigned char* smem) {
;     ...
;             if (ch + 1 < 128) {
;                 const size_t go = ((size_t)(b * 2048 + (ch + 1) * 16 + tp)) * 1024 + col;
;                 pr[0] = *(const u32x2*)(r16 + go); pr[1] = *(const u32x2*)(k16 + go); pr[2] = *(const u32x2*)(v16 + go);
;                 pr[3] = *(const u32x2*)(e16 + go); pr[4] = *(const u32x2*)(a16 + go); pr[5] = *(const u32x2*)(g16 + go);
;             }
;             __syncthreads();
; #pragma unroll 2
;             for (int t = 0; t < 16; ++t) {
;                 const float* op = OPS + t * 320 + kq * 16;
;                 f32x4 A4[4], B4[4], W4[4], K4[4], R4[4];
; #pragma unroll
;                 for (int i = 0; i < 4; ++i) A4[i] = *(const f32x4*)(op + i * 4);
; #pragma unroll
;                 for (int i = 0; i < 4; ++i) { W4[i] = *(const f32x4*)(op + 128 + i * 4); B4[i] = *(const f32x4*)(op + 64 + i * 4); K4[i] = *(const f32x4*)(op + 192 + i * 4); }
; #pragma unroll
;                 for (int i = 0; i < 4; ++i) R4[i] = *(const f32x4*)(op + 256 + i * 4);
;                 const float vv = VB[t * 64 + vrow];
;                 f32x2 s0 = {0.f, 0.f}, s1 = {0.f, 0.f};
; #pragma unroll
;                 for (int i = 0; i < 4; ++i) { s0 += S[2 * i] * (f32x2){A4[i][0], A4[i][1]}; s1 += S[2 * i + 1] * (f32x2){A4[i][2], A4[i][3]}; }
;                 const float sa = red4((s0[0] + s0[1]) + (s1[0] + s1[1]));
;                 const f32x2 sa2 = {sa, sa}, vv2 = {vv, vv};
; #pragma unroll
;                 for (int i = 0; i < 4; ++i) {
;                     S[2 * i] = S[2 * i] * (f32x2){W4[i][0], W4[i][1]} + sa2 * (f32x2){B4[i][0], B4[i][1]} + vv2 * (f32x2){K4[i][0], K4[i][1]};
;                     S[2 * i + 1] = S[2 * i + 1] * (f32x2){W4[i][2], W4[i][3]} + sa2 * (f32x2){B4[i][2], B4[i][3]} + vv2 * (f32x2){K4[i][2], K4[i][3]};
.LBB0_509:
	v_lshlrev_b32_e32 v66, 2, v226
	v_and_b32_e32 v66, 32, v66
	v_add3_u32 v64, v23, v59, v66
	v_and_b32_e32 v66, 8, v226
	v_sub_u32_e32 v65, v62, v66
	v_lshl_add_u32 v65, s10, 2, v65
	s_movk_i32 s7, 0xf000
	s_waitcnt lgkmcnt(0)
	s_barrier
	v_add_u32_e32 v66, s7, v65
	v_add_u32_e32 v67, 0x6200, v66
	v_add_u32_e32 v172, 0x8000, v66
	ds_read_b128 v[68:71], v64
	ds_read_b128 v[72:75], v64 offset:16
	ds_read_b128 v[76:79], v64 offset:256
	ds_read_b128 v[80:83], v64 offset:272
	ds_read_b128 v[84:87], v64 offset:512
	ds_read_b128 v[88:91], v64 offset:528
	ds_read_b128 v[92:95], v64 offset:768
	ds_read_b128 v[96:99], v64 offset:784
	ds_read_b128 v[100:103], v64 offset:1024
	ds_read_b128 v[104:107], v64 offset:1040
	ds_read_b32 v108, v66 offset:24576
	ds_read_b32 v109, v66 offset:24584
	s_waitcnt lgkmcnt(0)
	ds_read_b128 v[112:115], v64 offset:1280
	ds_read_b128 v[116:119], v64 offset:1296
	ds_read_b128 v[120:123], v64 offset:1536
	ds_read_b128 v[124:127], v64 offset:1552
	ds_read_b128 v[128:131], v64 offset:1792
	ds_read_b128 v[132:135], v64 offset:1808
	ds_read_b128 v[136:139], v64 offset:2048
	ds_read_b128 v[140:143], v64 offset:2064
	ds_read_b128 v[144:147], v64 offset:2304
	ds_read_b128 v[148:151], v64 offset:2320
	ds_read_b32 v152, v66 offset:24832
	ds_read_b32 v153, v66 offset:24840
	v_pk_mul_f32 v[156:157], v[38:39], v[68:69]
	v_pk_mul_f32 v[158:159], v[46:47], v[68:69]
	v_pk_fma_f32 v[156:157], v[40:41], v[70:71], v[156:157]
	v_pk_fma_f32 v[158:159], v[48:49], v[70:71], v[158:159]
	v_pk_fma_f32 v[156:157], v[42:43], v[72:73], v[156:157]
	v_pk_fma_f32 v[158:159], v[50:51], v[72:73], v[158:159]
	v_pk_fma_f32 v[156:157], v[44:45], v[74:75], v[156:157]
	v_pk_fma_f32 v[158:159], v[52:53], v[74:75], v[158:159]
	v_add_f32_e32 v156, v156, v157
	v_add_f32_e32 v158, v158, v159
	v_pk_mul_f32 v[38:39], v[38:39], v[84:85]
	v_add_f32_dpp v168, v156, v156 quad_perm:[1,0,3,2] row_mask:0xf bank_mask:0xf bound_ctrl:1
	v_add_f32_dpp v169, v158, v158 quad_perm:[1,0,3,2] row_mask:0xf bank_mask:0xf bound_ctrl:1
	v_pk_mul_f32 v[46:47], v[46:47], v[84:85]
	v_add_f32_dpp v170, v168, v168 quad_perm:[2,3,0,1] row_mask:0xf bank_mask:0xf bound_ctrl:1
	v_add_f32_dpp v171, v169, v169 quad_perm:[2,3,0,1] row_mask:0xf bank_mask:0xf bound_ctrl:1
	v_pk_mul_f32 v[40:41], v[40:41], v[86:87]
	v_add_f32_dpp v160, v170, v170 row_ror:8 row_mask:0xf bank_mask:0xf
	v_add_f32_dpp v162, v171, v171 row_ror:8 row_mask:0xf bank_mask:0xf
	v_pk_mul_f32 v[48:49], v[48:49], v[86:87]
	v_pk_mul_f32 v[42:43], v[42:43], v[88:89]
	v_pk_mul_f32 v[50:51], v[50:51], v[88:89]
	v_pk_mul_f32 v[44:45], v[44:45], v[90:91]
	v_pk_mul_f32 v[52:53], v[52:53], v[90:91]
	v_pk_fma_f32 v[38:39], v[76:77], v[160:161], v[38:39] op_sel_hi:[1,0,1]
	v_pk_fma_f32 v[46:47], v[76:77], v[162:163], v[46:47] op_sel_hi:[1,0,1]
	v_pk_fma_f32 v[40:41], v[78:79], v[160:161], v[40:41] op_sel_hi:[1,0,1]
	v_pk_fma_f32 v[48:49], v[78:79], v[162:163], v[48:49] op_sel_hi:[1,0,1]
	v_pk_fma_f32 v[42:43], v[80:81], v[160:161], v[42:43] op_sel_hi:[1,0,1]
	v_pk_fma_f32 v[50:51], v[80:81], v[162:163], v[50:51] op_sel_hi:[1,0,1]
	v_pk_fma_f32 v[44:45], v[82:83], v[160:161], v[44:45] op_sel_hi:[1,0,1]
	v_pk_fma_f32 v[52:53], v[82:83], v[162:163], v[52:53] op_sel_hi:[1,0,1]
	v_pk_fma_f32 v[38:39], v[92:93], v[108:109], v[38:39] op_sel_hi:[1,0,1]
	v_pk_fma_f32 v[46:47], v[92:93], v[108:109], v[46:47] op_sel:[0,1,0] op_sel_hi:[1,1,1]
	v_pk_fma_f32 v[40:41], v[94:95], v[108:109], v[40:41] op_sel_hi:[1,0,1]
	v_pk_fma_f32 v[48:49], v[94:95], v[108:109], v[48:49] op_sel:[0,1,0] op_sel_hi:[1,1,1]
	v_pk_fma_f32 v[42:43], v[96:97], v[108:109], v[42:43] op_sel_hi:[1,0,1]
	v_pk_fma_f32 v[50:51], v[96:97], v[108:109], v[50:51] op_sel:[0,1,0] op_sel_hi:[1,1,1]
	v_pk_fma_f32 v[44:45], v[98:99], v[108:109], v[44:45] op_sel_hi:[1,0,1]
	v_pk_fma_f32 v[52:53], v[98:99], v[108:109], v[52:53] op_sel:[0,1,0] op_sel_hi:[1,1,1]
	v_pk_mul_f32 v[164:165], v[38:39], v[100:101]
	v_pk_mul_f32 v[166:167], v[46:47], v[100:101]
	v_pk_fma_f32 v[164:165], v[40:41], v[102:103], v[164:165]
	v_pk_fma_f32 v[166:167], v[48:49], v[102:103], v[166:167]
	v_pk_fma_f32 v[164:165], v[42:43], v[104:105], v[164:165]
	v_pk_fma_f32 v[166:167], v[50:51], v[104:105], v[166:167]
	v_pk_fma_f32 v[164:165], v[44:45], v[106:107], v[164:165]
	v_pk_fma_f32 v[166:167], v[52:53], v[106:107], v[166:167]
	v_add_f32_e32 v164, v164, v165
	v_add_f32_e32 v166, v166, v167
	s_waitcnt lgkmcnt(0)
; __device__ __forceinline__ float red4(float x) { x += dppf(x, 0); x += dppf(x, 1); return x; }
; __device__ __forceinline__ void scan_phase(const Params& p, int j, unsigned char* smem) {
;     ...
;             for (int t = 0; t < 16; ++t) {
;                 const float* op = OPS + t * 320 + kq * 16;
;                 f32x4 A4[4], B4[4], W4[4], K4[4], R4[4];
; #pragma unroll
;                 for (int i = 0; i < 4; ++i) A4[i] = *(const f32x4*)(op + i * 4);
; #pragma unroll
;                 for (int i = 0; i < 4; ++i) { W4[i] = *(const f32x4*)(op + 128 + i * 4); B4[i] = *(const f32x4*)(op + 64 + i * 4); K4[i] = *(const f32x4*)(op + 192 + i * 4); }
; #pragma unroll
;                 for (int i = 0; i < 4; ++i) R4[i] = *(const f32x4*)(op + 256 + i * 4);
;                 const float vv = VB[t * 64 + vrow];
;                 f32x2 s0 = {0.f, 0.f}, s1 = {0.f, 0.f};
; #pragma unroll
;                 for (int i = 0; i < 4; ++i) { s0 += S[2 * i] * (f32x2){A4[i][0], A4[i][1]}; s1 += S[2 * i + 1] * (f32x2){A4[i][2], A4[i][3]}; }
;                 const float sa = red4((s0[0] + s0[1]) + (s1[0] + s1[1]));
;                 const f32x2 sa2 = {sa, sa}, vv2 = {vv, vv};
; #pragma unroll
;                 for (int i = 0; i < 4; ++i) {
;                     S[2 * i] = S[2 * i] * (f32x2){W4[i][0], W4[i][1]} + sa2 * (f32x2){B4[i][0], B4[i][1]} + vv2 * (f32x2){K4[i][0], K4[i][1]};
;                     S[2 * i + 1] = S[2 * i + 1] * (f32x2){W4[i][2], W4[i][3]} + sa2 * (f32x2){B4[i][2], B4[i][3]} + vv2 * (f32x2){K4[i][2], K4[i][3]};
;                 }
;                 f32x2 y0 = {0.f, 0.f}, y1 = {0.f, 0.f};
; #pragma unroll
;                 for (int i = 0; i < 4; ++i) { y0 += S[2 * i] * (f32x2){R4[i][0], R4[i][1]}; y1 += S[2 * i + 1] * (f32x2){R4[i][2], R4[i][3]}; }
;                 const float y = red4((y0[0] + y0[1]) + (y1[0] + y1[1]));
;                 if (kq == 0) YB[t * 64 + vrow] = y;
	ds_read_b128 v[68:71], v64 offset:2560
	v_add_f32_dpp v168, v164, v164 quad_perm:[1,0,3,2] row_mask:0xf bank_mask:0xf bound_ctrl:1
	v_add_f32_dpp v169, v166, v166 quad_perm:[1,0,3,2] row_mask:0xf bank_mask:0xf bound_ctrl:1
	ds_read_b128 v[72:75], v64 offset:2576
	v_add_f32_dpp v170, v168, v168 quad_perm:[2,3,0,1] row_mask:0xf bank_mask:0xf bound_ctrl:1
	v_add_f32_dpp v171, v169, v169 quad_perm:[2,3,0,1] row_mask:0xf bank_mask:0xf bound_ctrl:1
	ds_read_b128 v[76:79], v64 offset:2816
	v_add_f32_dpp v164, v170, v170 row_ror:8 row_mask:0xf bank_mask:0xf
	v_add_f32_dpp v166, v171, v171 row_ror:8 row_mask:0xf bank_mask:0xf
	ds_read_b128 v[80:83], v64 offset:2832
	ds_read_b128 v[84:87], v64 offset:3072
	ds_read_b128 v[88:91], v64 offset:3088
	ds_read_b128 v[92:95], v64 offset:3328
	ds_read_b128 v[96:99], v64 offset:3344
	ds_read_b128 v[100:103], v64 offset:3584
	ds_read_b128 v[104:107], v64 offset:3600
	ds_read2_b32 v[108:109], v67 offset0:0 offset1:2
	ds_write2_b32 v172, v164, v166 offset0:0 offset1:2
	v_pk_mul_f32 v[156:157], v[38:39], v[112:113]
	v_pk_mul_f32 v[158:159], v[46:47], v[112:113]
	v_pk_fma_f32 v[156:157], v[40:41], v[114:115], v[156:157]
	v_pk_fma_f32 v[158:159], v[48:49], v[114:115], v[158:159]
	v_pk_fma_f32 v[156:157], v[42:43], v[116:117], v[156:157]
	v_pk_fma_f32 v[158:159], v[50:51], v[116:117], v[158:159]
	v_pk_fma_f32 v[156:157], v[44:45], v[118:119], v[156:157]
	v_pk_fma_f32 v[158:159], v[52:53], v[118:119], v[158:159]
	v_add_f32_e32 v156, v156, v157
	v_add_f32_e32 v158, v158, v159
	v_pk_mul_f32 v[38:39], v[38:39], v[128:129]
	v_add_f32_dpp v168, v156, v156 quad_perm:[1,0,3,2] row_mask:0xf bank_mask:0xf bound_ctrl:1
	v_add_f32_dpp v169, v158, v158 quad_perm:[1,0,3,2] row_mask:0xf bank_mask:0xf bound_ctrl:1
	v_pk_mul_f32 v[46:47], v[46:47], v[128:129]
	v_add_f32_dpp v170, v168, v168 quad_perm:[2,3,0,1] row_mask:0xf bank_mask:0xf bound_ctrl:1
	v_add_f32_dpp v171, v169, v169 quad_perm:[2,3,0,1] row_mask:0xf bank_mask:0xf bound_ctrl:1
	v_pk_mul_f32 v[40:41], v[40:41], v[130:131]
	v_add_f32_dpp v160, v170, v170 row_ror:8 row_mask:0xf bank_mask:0xf
	v_add_f32_dpp v162, v171, v171 row_ror:8 row_mask:0xf bank_mask:0xf
	v_pk_mul_f32 v[48:49], v[48:49], v[130:131]
	v_pk_mul_f32 v[42:43], v[42:43], v[132:133]
	v_pk_mul_f32 v[50:51], v[50:51], v[132:133]
	v_pk_mul_f32 v[44:45], v[44:45], v[134:135]
	v_pk_mul_f32 v[52:53], v[52:53], v[134:135]
	v_pk_fma_f32 v[38:39], v[120:121], v[160:161], v[38:39] op_sel_hi:[1,0,1]
	v_pk_fma_f32 v[46:47], v[120:121], v[162:163], v[46:47] op_sel_hi:[1,0,1]
	v_pk_fma_f32 v[40:41], v[122:123], v[160:161], v[40:41] op_sel_hi:[1,0,1]
	v_pk_fma_f32 v[48:49], v[122:123], v[162:163], v[48:49] op_sel_hi:[1,0,1]
	v_pk_fma_f32 v[42:43], v[124:125], v[160:161], v[42:43] op_sel_hi:[1,0,1]
	v_pk_fma_f32 v[50:51], v[124:125], v[162:163], v[50:51] op_sel_hi:[1,0,1]
	v_pk_fma_f32 v[44:45], v[126:127], v[160:161], v[44:45] op_sel_hi:[1,0,1]
	v_pk_fma_f32 v[52:53], v[126:127], v[162:163], v[52:53] op_sel_hi:[1,0,1]
	v_pk_fma_f32 v[38:39], v[136:137], v[152:153], v[38:39] op_sel_hi:[1,0,1]
	v_pk_fma_f32 v[46:47], v[136:137], v[152:153], v[46:47] op_sel:[0,1,0] op_sel_hi:[1,1,1]
	v_pk_fma_f32 v[40:41], v[138:139], v[152:153], v[40:41] op_sel_hi:[1,0,1]
	v_pk_fma_f32 v[48:49], v[138:139], v[152:153], v[48:49] op_sel:[0,1,0] op_sel_hi:[1,1,1]
	v_pk_fma_f32 v[42:43], v[140:141], v[152:153], v[42:43] op_sel_hi:[1,0,1]
	v_pk_fma_f32 v[50:51], v[140:141], v[152:153], v[50:51] op_sel:[0,1,0] op_sel_hi:[1,1,1]
	v_pk_fma_f32 v[44:45], v[142:143], v[152:153], v[44:45] op_sel_hi:[1,0,1]
	v_pk_fma_f32 v[52:53], v[142:143], v[152:153], v[52:53] op_sel:[0,1,0] op_sel_hi:[1,1,1]
	v_pk_mul_f32 v[164:165], v[38:39], v[144:145]
	v_pk_mul_f32 v[166:167], v[46:47], v[144:145]
	v_pk_fma_f32 v[164:165], v[40:41], v[146:147], v[164:165]
	v_pk_fma_f32 v[166:167], v[48:49], v[146:147], v[166:167]
	v_pk_fma_f32 v[164:165], v[42:43], v[148:149], v[164:165]
	v_pk_fma_f32 v[166:167], v[50:51], v[148:149], v[166:167]
	v_pk_fma_f32 v[164:165], v[44:45], v[150:151], v[164:165]
	v_pk_fma_f32 v[166:167], v[52:53], v[150:151], v[166:167]
	v_add_f32_e32 v164, v164, v165
	v_add_f32_e32 v166, v166, v167
	s_waitcnt lgkmcnt(0)
	ds_read_b128 v[112:115], v64 offset:3840
	v_add_f32_dpp v168, v164, v164 quad_perm:[1,0,3,2] row_mask:0xf bank_mask:0xf bound_ctrl:1
	v_add_f32_dpp v169, v166, v166 quad_perm:[1,0,3,2] row_mask:0xf bank_mask:0xf bound_ctrl:1
	ds_read_b128 v[116:119], v64 offset:3856
	v_add_f32_dpp v170, v168, v168 quad_perm:[2,3,0,1] row_mask:0xf bank_mask:0xf bound_ctrl:1
	v_add_f32_dpp v171, v169, v169 quad_perm:[2,3,0,1] row_mask:0xf bank_mask:0xf bound_ctrl:1
	ds_read_b128 v[120:123], v64 offset:4096
	v_add_f32_dpp v164, v170, v170 row_ror:8 row_mask:0xf bank_mask:0xf
	v_add_f32_dpp v166, v171, v171 row_ror:8 row_mask:0xf bank_mask:0xf
	ds_read_b128 v[124:127], v64 offset:4112
	ds_read_b128 v[128:131], v64 offset:4352
	ds_read_b128 v[132:135], v64 offset:4368
	ds_read_b128 v[136:139], v64 offset:4608
	ds_read_b128 v[140:143], v64 offset:4624
	ds_read_b128 v[144:147], v64 offset:4864
	ds_read_b128 v[148:151], v64 offset:4880
	ds_read2_b32 v[152:153], v67 offset0:64 offset1:66
	ds_write2_b32 v172, v164, v166 offset0:64 offset1:66
	v_pk_mul_f32 v[156:157], v[38:39], v[68:69]
	v_pk_mul_f32 v[158:159], v[46:47], v[68:69]
	v_pk_fma_f32 v[156:157], v[40:41], v[70:71], v[156:157]
	v_pk_fma_f32 v[158:159], v[48:49], v[70:71], v[158:159]
	v_pk_fma_f32 v[156:157], v[42:43], v[72:73], v[156:157]
	v_pk_fma_f32 v[158:159], v[50:51], v[72:73], v[158:159]
	v_pk_fma_f32 v[156:157], v[44:45], v[74:75], v[156:157]
	v_pk_fma_f32 v[158:159], v[52:53], v[74:75], v[158:159]
; __device__ __forceinline__ float red4(float x) { x += dppf(x, 0); x += dppf(x, 1); return x; }
; __device__ __forceinline__ void scan_phase(const Params& p, int j, unsigned char* smem) {
;     ...
;             for (int t = 0; t < 16; ++t) {
;                 const float* op = OPS + t * 320 + kq * 16;
;                 f32x4 A4[4], B4[4], W4[4], K4[4], R4[4];
; #pragma unroll
;                 for (int i = 0; i < 4; ++i) A4[i] = *(const f32x4*)(op + i * 4);
; #pragma unroll
;                 for (int i = 0; i < 4; ++i) { W4[i] = *(const f32x4*)(op + 128 + i * 4); B4[i] = *(const f32x4*)(op + 64 + i * 4); K4[i] = *(const f32x4*)(op + 192 + i * 4); }
; #pragma unroll
;                 for (int i = 0; i < 4; ++i) R4[i] = *(const f32x4*)(op + 256 + i * 4);
;                 const float vv = VB[t * 64 + vrow];
;                 f32x2 s0 = {0.f, 0.f}, s1 = {0.f, 0.f};
; #pragma unroll
;                 for (int i = 0; i < 4; ++i) { s0 += S[2 * i] * (f32x2){A4[i][0], A4[i][1]}; s1 += S[2 * i + 1] * (f32x2){A4[i][2], A4[i][3]}; }
;                 const float sa = red4((s0[0] + s0[1]) + (s1[0] + s1[1]));
;                 const f32x2 sa2 = {sa, sa}, vv2 = {vv, vv};
; #pragma unroll
;                 for (int i = 0; i < 4; ++i) {
;                     S[2 * i] = S[2 * i] * (f32x2){W4[i][0], W4[i][1]} + sa2 * (f32x2){B4[i][0], B4[i][1]} + vv2 * (f32x2){K4[i][0], K4[i][1]};
;                     S[2 * i + 1] = S[2 * i + 1] * (f32x2){W4[i][2], W4[i][3]} + sa2 * (f32x2){B4[i][2], B4[i][3]} + vv2 * (f32x2){K4[i][2], K4[i][3]};
;                 }
;                 f32x2 y0 = {0.f, 0.f}, y1 = {0.f, 0.f};
; #pragma unroll
;                 for (int i = 0; i < 4; ++i) { y0 += S[2 * i] * (f32x2){R4[i][0], R4[i][1]}; y1 += S[2 * i + 1] * (f32x2){R4[i][2], R4[i][3]}; }
;                 const float y = red4((y0[0] + y0[1]) + (y1[0] + y1[1]));
;                 if (kq == 0) YB[t * 64 + vrow] = y;
	v_add_f32_e32 v156, v156, v157
	v_add_f32_e32 v158, v158, v159
	v_pk_mul_f32 v[38:39], v[38:39], v[84:85]
	v_add_f32_dpp v168, v156, v156 quad_perm:[1,0,3,2] row_mask:0xf bank_mask:0xf bound_ctrl:1
	v_add_f32_dpp v169, v158, v158 quad_perm:[1,0,3,2] row_mask:0xf bank_mask:0xf bound_ctrl:1
	v_pk_mul_f32 v[46:47], v[46:47], v[84:85]
	v_add_f32_dpp v170, v168, v168 quad_perm:[2,3,0,1] row_mask:0xf bank_mask:0xf bound_ctrl:1
	v_add_f32_dpp v171, v169, v169 quad_perm:[2,3,0,1] row_mask:0xf bank_mask:0xf bound_ctrl:1
	v_pk_mul_f32 v[40:41], v[40:41], v[86:87]
	v_add_f32_dpp v160, v170, v170 row_ror:8 row_mask:0xf bank_mask:0xf
	v_add_f32_dpp v162, v171, v171 row_ror:8 row_mask:0xf bank_mask:0xf
	v_pk_mul_f32 v[48:49], v[48:49], v[86:87]
	v_pk_mul_f32 v[42:43], v[42:43], v[88:89]
	v_pk_mul_f32 v[50:51], v[50:51], v[88:89]
	v_pk_mul_f32 v[44:45], v[44:45], v[90:91]
	v_pk_mul_f32 v[52:53], v[52:53], v[90:91]
	v_pk_fma_f32 v[38:39], v[76:77], v[160:161], v[38:39] op_sel_hi:[1,0,1]
	v_pk_fma_f32 v[46:47], v[76:77], v[162:163], v[46:47] op_sel_hi:[1,0,1]
	v_pk_fma_f32 v[40:41], v[78:79], v[160:161], v[40:41] op_sel_hi:[1,0,1]
	v_pk_fma_f32 v[48:49], v[78:79], v[162:163], v[48:49] op_sel_hi:[1,0,1]
	v_pk_fma_f32 v[42:43], v[80:81], v[160:161], v[42:43] op_sel_hi:[1,0,1]
	v_pk_fma_f32 v[50:51], v[80:81], v[162:163], v[50:51] op_sel_hi:[1,0,1]
	v_pk_fma_f32 v[44:45], v[82:83], v[160:161], v[44:45] op_sel_hi:[1,0,1]
	v_pk_fma_f32 v[52:53], v[82:83], v[162:163], v[52:53] op_sel_hi:[1,0,1]
	v_pk_fma_f32 v[38:39], v[92:93], v[108:109], v[38:39] op_sel_hi:[1,0,1]
	v_pk_fma_f32 v[46:47], v[92:93], v[108:109], v[46:47] op_sel:[0,1,0] op_sel_hi:[1,1,1]
	v_pk_fma_f32 v[40:41], v[94:95], v[108:109], v[40:41] op_sel_hi:[1,0,1]
	v_pk_fma_f32 v[48:49], v[94:95], v[108:109], v[48:49] op_sel:[0,1,0] op_sel_hi:[1,1,1]
	v_pk_fma_f32 v[42:43], v[96:97], v[108:109], v[42:43] op_sel_hi:[1,0,1]
	v_pk_fma_f32 v[50:51], v[96:97], v[108:109], v[50:51] op_sel:[0,1,0] op_sel_hi:[1,1,1]
	v_pk_fma_f32 v[44:45], v[98:99], v[108:109], v[44:45] op_sel_hi:[1,0,1]
	v_pk_fma_f32 v[52:53], v[98:99], v[108:109], v[52:53] op_sel:[0,1,0] op_sel_hi:[1,1,1]
	v_pk_mul_f32 v[164:165], v[38:39], v[100:101]
	v_pk_mul_f32 v[166:167], v[46:47], v[100:101]
	v_pk_fma_f32 v[164:165], v[40:41], v[102:103], v[164:165]
	v_pk_fma_f32 v[166:167], v[48:49], v[102:103], v[166:167]
	v_pk_fma_f32 v[164:165], v[42:43], v[104:105], v[164:165]
	v_pk_fma_f32 v[166:167], v[50:51], v[104:105], v[166:167]
	v_pk_fma_f32 v[164:165], v[44:45], v[106:107], v[164:165]
	v_pk_fma_f32 v[166:167], v[52:53], v[106:107], v[166:167]
	v_add_f32_e32 v164, v164, v165
	v_add_f32_e32 v166, v166, v167
	s_waitcnt lgkmcnt(0)
	ds_read_b128 v[68:71], v64 offset:5120
	v_add_f32_dpp v168, v164, v164 quad_perm:[1,0,3,2] row_mask:0xf bank_mask:0xf bound_ctrl:1
	v_add_f32_dpp v169, v166, v166 quad_perm:[1,0,3,2] row_mask:0xf bank_mask:0xf bound_ctrl:1
	ds_read_b128 v[72:75], v64 offset:5136
	v_add_f32_dpp v170, v168, v168 quad_perm:[2,3,0,1] row_mask:0xf bank_mask:0xf bound_ctrl:1
	v_add_f32_dpp v171, v169, v169 quad_perm:[2,3,0,1] row_mask:0xf bank_mask:0xf bound_ctrl:1
	ds_read_b128 v[76:79], v64 offset:5376
	v_add_f32_dpp v164, v170, v170 row_ror:8 row_mask:0xf bank_mask:0xf
	v_add_f32_dpp v166, v171, v171 row_ror:8 row_mask:0xf bank_mask:0xf
	ds_read_b128 v[80:83], v64 offset:5392
	ds_read_b128 v[84:87], v64 offset:5632
	ds_read_b128 v[88:91], v64 offset:5648
	ds_read_b128 v[92:95], v64 offset:5888
	ds_read_b128 v[96:99], v64 offset:5904
	ds_read_b128 v[100:103], v64 offset:6144
	ds_read_b128 v[104:107], v64 offset:6160
	ds_read2_b32 v[108:109], v67 offset0:128 offset1:130
	ds_write2_b32 v172, v164, v166 offset0:128 offset1:130
	v_pk_mul_f32 v[156:157], v[38:39], v[112:113]
	v_pk_mul_f32 v[158:159], v[46:47], v[112:113]
	v_pk_fma_f32 v[156:157], v[40:41], v[114:115], v[156:157]
	v_pk_fma_f32 v[158:159], v[48:49], v[114:115], v[158:159]
	v_pk_fma_f32 v[156:157], v[42:43], v[116:117], v[156:157]
	v_pk_fma_f32 v[158:159], v[50:51], v[116:117], v[158:159]
	v_pk_fma_f32 v[156:157], v[44:45], v[118:119], v[156:157]
	v_pk_fma_f32 v[158:159], v[52:53], v[118:119], v[158:159]
	v_add_f32_e32 v156, v156, v157
	v_add_f32_e32 v158, v158, v159
	v_pk_mul_f32 v[38:39], v[38:39], v[128:129]
	v_add_f32_dpp v168, v156, v156 quad_perm:[1,0,3,2] row_mask:0xf bank_mask:0xf bound_ctrl:1
	v_add_f32_dpp v169, v158, v158 quad_perm:[1,0,3,2] row_mask:0xf bank_mask:0xf bound_ctrl:1
	v_pk_mul_f32 v[46:47], v[46:47], v[128:129]
	v_add_f32_dpp v170, v168, v168 quad_perm:[2,3,0,1] row_mask:0xf bank_mask:0xf bound_ctrl:1
	v_add_f32_dpp v171, v169, v169 quad_perm:[2,3,0,1] row_mask:0xf bank_mask:0xf bound_ctrl:1
	v_pk_mul_f32 v[40:41], v[40:41], v[130:131]
	v_add_f32_dpp v160, v170, v170 row_ror:8 row_mask:0xf bank_mask:0xf
	v_add_f32_dpp v162, v171, v171 row_ror:8 row_mask:0xf bank_mask:0xf
	v_pk_mul_f32 v[48:49], v[48:49], v[130:131]
	v_pk_mul_f32 v[42:43], v[42:43], v[132:133]
	v_pk_mul_f32 v[50:51], v[50:51], v[132:133]
	v_pk_mul_f32 v[44:45], v[44:45], v[134:135]
	v_pk_mul_f32 v[52:53], v[52:53], v[134:135]
	v_pk_fma_f32 v[38:39], v[120:121], v[160:161], v[38:39] op_sel_hi:[1,0,1]
	v_pk_fma_f32 v[46:47], v[120:121], v[162:163], v[46:47] op_sel_hi:[1,0,1]
	v_pk_fma_f32 v[40:41], v[122:123], v[160:161], v[40:41] op_sel_hi:[1,0,1]
	v_pk_fma_f32 v[48:49], v[122:123], v[162:163], v[48:49] op_sel_hi:[1,0,1]
	v_pk_fma_f32 v[42:43], v[124:125], v[160:161], v[42:43] op_sel_hi:[1,0,1]
	v_pk_fma_f32 v[50:51], v[124:125], v[162:163], v[50:51] op_sel_hi:[1,0,1]
	v_pk_fma_f32 v[44:45], v[126:127], v[160:161], v[44:45] op_sel_hi:[1,0,1]
	v_pk_fma_f32 v[52:53], v[126:127], v[162:163], v[52:53] op_sel_hi:[1,0,1]
	v_pk_fma_f32 v[38:39], v[136:137], v[152:153], v[38:39] op_sel_hi:[1,0,1]
	v_pk_fma_f32 v[46:47], v[136:137], v[152:153], v[46:47] op_sel:[0,1,0] op_sel_hi:[1,1,1]
	v_pk_fma_f32 v[40:41], v[138:139], v[152:153], v[40:41] op_sel_hi:[1,0,1]
	v_pk_fma_f32 v[48:49], v[138:139], v[152:153], v[48:49] op_sel:[0,1,0] op_sel_hi:[1,1,1]
	v_pk_fma_f32 v[42:43], v[140:141], v[152:153], v[42:43] op_sel_hi:[1,0,1]
	v_pk_fma_f32 v[50:51], v[140:141], v[152:153], v[50:51] op_sel:[0,1,0] op_sel_hi:[1,1,1]
	v_pk_fma_f32 v[44:45], v[142:143], v[152:153], v[44:45] op_sel_hi:[1,0,1]
	v_pk_fma_f32 v[52:53], v[142:143], v[152:153], v[52:53] op_sel:[0,1,0] op_sel_hi:[1,1,1]
	v_pk_mul_f32 v[164:165], v[38:39], v[144:145]
	v_pk_mul_f32 v[166:167], v[46:47], v[144:145]
	v_pk_fma_f32 v[164:165], v[40:41], v[146:147], v[164:165]
	v_pk_fma_f32 v[166:167], v[48:49], v[146:147], v[166:167]
	v_pk_fma_f32 v[164:165], v[42:43], v[148:149], v[164:165]
	v_pk_fma_f32 v[166:167], v[50:51], v[148:149], v[166:167]
	v_pk_fma_f32 v[164:165], v[44:45], v[150:151], v[164:165]
	v_pk_fma_f32 v[166:167], v[52:53], v[150:151], v[166:167]
	v_add_f32_e32 v164, v164, v165
	v_add_f32_e32 v166, v166, v167
	s_waitcnt lgkmcnt(0)
; __device__ __forceinline__ float red4(float x) { x += dppf(x, 0); x += dppf(x, 1); return x; }
; __device__ __forceinline__ void scan_phase(const Params& p, int j, unsigned char* smem) {
;     ...
;             for (int t = 0; t < 16; ++t) {
;                 const float* op = OPS + t * 320 + kq * 16;
;                 f32x4 A4[4], B4[4], W4[4], K4[4], R4[4];
; #pragma unroll
;                 for (int i = 0; i < 4; ++i) A4[i] = *(const f32x4*)(op + i * 4);
; #pragma unroll
;                 for (int i = 0; i < 4; ++i) { W4[i] = *(const f32x4*)(op + 128 + i * 4); B4[i] = *(const f32x4*)(op + 64 + i * 4); K4[i] = *(const f32x4*)(op + 192 + i * 4); }
; #pragma unroll
;                 for (int i = 0; i < 4; ++i) R4[i] = *(const f32x4*)(op + 256 + i * 4);
;                 const float vv = VB[t * 64 + vrow];
;                 f32x2 s0 = {0.f, 0.f}, s1 = {0.f, 0.f};
; #pragma unroll
;                 for (int i = 0; i < 4; ++i) { s0 += S[2 * i] * (f32x2){A4[i][0], A4[i][1]}; s1 += S[2 * i + 1] * (f32x2){A4[i][2], A4[i][3]}; }
;                 const float sa = red4((s0[0] + s0[1]) + (s1[0] + s1[1]));
;                 const f32x2 sa2 = {sa, sa}, vv2 = {vv, vv};
; #pragma unroll
;                 for (int i = 0; i < 4; ++i) {
;                     S[2 * i] = S[2 * i] * (f32x2){W4[i][0], W4[i][1]} + sa2 * (f32x2){B4[i][0], B4[i][1]} + vv2 * (f32x2){K4[i][0], K4[i][1]};
;                     S[2 * i + 1] = S[2 * i + 1] * (f32x2){W4[i][2], W4[i][3]} + sa2 * (f32x2){B4[i][2], B4[i][3]} + vv2 * (f32x2){K4[i][2], K4[i][3]};
;                 }
;                 f32x2 y0 = {0.f, 0.f}, y1 = {0.f, 0.f};
; #pragma unroll
;                 for (int i = 0; i < 4; ++i) { y0 += S[2 * i] * (f32x2){R4[i][0], R4[i][1]}; y1 += S[2 * i + 1] * (f32x2){R4[i][2], R4[i][3]}; }
;                 const float y = red4((y0[0] + y0[1]) + (y1[0] + y1[1]));
;                 if (kq == 0) YB[t * 64 + vrow] = y;
	ds_read_b128 v[112:115], v64 offset:6400
	v_add_f32_dpp v168, v164, v164 quad_perm:[1,0,3,2] row_mask:0xf bank_mask:0xf bound_ctrl:1
	v_add_f32_dpp v169, v166, v166 quad_perm:[1,0,3,2] row_mask:0xf bank_mask:0xf bound_ctrl:1
	ds_read_b128 v[116:119], v64 offset:6416
	v_add_f32_dpp v170, v168, v168 quad_perm:[2,3,0,1] row_mask:0xf bank_mask:0xf bound_ctrl:1
	v_add_f32_dpp v171, v169, v169 quad_perm:[2,3,0,1] row_mask:0xf bank_mask:0xf bound_ctrl:1
	ds_read_b128 v[120:123], v64 offset:6656
	v_add_f32_dpp v164, v170, v170 row_ror:8 row_mask:0xf bank_mask:0xf
	v_add_f32_dpp v166, v171, v171 row_ror:8 row_mask:0xf bank_mask:0xf
	ds_read_b128 v[124:127], v64 offset:6672
	ds_read_b128 v[128:131], v64 offset:6912
	ds_read_b128 v[132:135], v64 offset:6928
	ds_read_b128 v[136:139], v64 offset:7168
	ds_read_b128 v[140:143], v64 offset:7184
	ds_read_b128 v[144:147], v64 offset:7424
	ds_read_b128 v[148:151], v64 offset:7440
	ds_read2_b32 v[152:153], v67 offset0:192 offset1:194
	ds_write2_b32 v172, v164, v166 offset0:192 offset1:194
	v_add_u32_e32 v67, 0x400, v67
	v_add_u32_e32 v172, 0x400, v172
	v_pk_mul_f32 v[156:157], v[38:39], v[68:69]
	v_pk_mul_f32 v[158:159], v[46:47], v[68:69]
	v_pk_fma_f32 v[156:157], v[40:41], v[70:71], v[156:157]
	v_pk_fma_f32 v[158:159], v[48:49], v[70:71], v[158:159]
	v_pk_fma_f32 v[156:157], v[42:43], v[72:73], v[156:157]
	v_pk_fma_f32 v[158:159], v[50:51], v[72:73], v[158:159]
	v_pk_fma_f32 v[156:157], v[44:45], v[74:75], v[156:157]
	v_pk_fma_f32 v[158:159], v[52:53], v[74:75], v[158:159]
	v_add_f32_e32 v156, v156, v157
	v_add_f32_e32 v158, v158, v159
	v_pk_mul_f32 v[38:39], v[38:39], v[84:85]
	v_add_f32_dpp v168, v156, v156 quad_perm:[1,0,3,2] row_mask:0xf bank_mask:0xf bound_ctrl:1
	v_add_f32_dpp v169, v158, v158 quad_perm:[1,0,3,2] row_mask:0xf bank_mask:0xf bound_ctrl:1
	v_pk_mul_f32 v[46:47], v[46:47], v[84:85]
	v_add_f32_dpp v170, v168, v168 quad_perm:[2,3,0,1] row_mask:0xf bank_mask:0xf bound_ctrl:1
	v_add_f32_dpp v171, v169, v169 quad_perm:[2,3,0,1] row_mask:0xf bank_mask:0xf bound_ctrl:1
	v_pk_mul_f32 v[40:41], v[40:41], v[86:87]
	v_add_f32_dpp v160, v170, v170 row_ror:8 row_mask:0xf bank_mask:0xf
	v_add_f32_dpp v162, v171, v171 row_ror:8 row_mask:0xf bank_mask:0xf
	v_pk_mul_f32 v[48:49], v[48:49], v[86:87]
	v_pk_mul_f32 v[42:43], v[42:43], v[88:89]
	v_pk_mul_f32 v[50:51], v[50:51], v[88:89]
	v_pk_mul_f32 v[44:45], v[44:45], v[90:91]
	v_pk_mul_f32 v[52:53], v[52:53], v[90:91]
	v_pk_fma_f32 v[38:39], v[76:77], v[160:161], v[38:39] op_sel_hi:[1,0,1]
	v_pk_fma_f32 v[46:47], v[76:77], v[162:163], v[46:47] op_sel_hi:[1,0,1]
	v_pk_fma_f32 v[40:41], v[78:79], v[160:161], v[40:41] op_sel_hi:[1,0,1]
	v_pk_fma_f32 v[48:49], v[78:79], v[162:163], v[48:49] op_sel_hi:[1,0,1]
	v_pk_fma_f32 v[42:43], v[80:81], v[160:161], v[42:43] op_sel_hi:[1,0,1]
	v_pk_fma_f32 v[50:51], v[80:81], v[162:163], v[50:51] op_sel_hi:[1,0,1]
	v_pk_fma_f32 v[44:45], v[82:83], v[160:161], v[44:45] op_sel_hi:[1,0,1]
	v_pk_fma_f32 v[52:53], v[82:83], v[162:163], v[52:53] op_sel_hi:[1,0,1]
	v_pk_fma_f32 v[38:39], v[92:93], v[108:109], v[38:39] op_sel_hi:[1,0,1]
	v_pk_fma_f32 v[46:47], v[92:93], v[108:109], v[46:47] op_sel:[0,1,0] op_sel_hi:[1,1,1]
	v_pk_fma_f32 v[40:41], v[94:95], v[108:109], v[40:41] op_sel_hi:[1,0,1]
	v_pk_fma_f32 v[48:49], v[94:95], v[108:109], v[48:49] op_sel:[0,1,0] op_sel_hi:[1,1,1]
	v_pk_fma_f32 v[42:43], v[96:97], v[108:109], v[42:43] op_sel_hi:[1,0,1]
	v_pk_fma_f32 v[50:51], v[96:97], v[108:109], v[50:51] op_sel:[0,1,0] op_sel_hi:[1,1,1]
	v_pk_fma_f32 v[44:45], v[98:99], v[108:109], v[44:45] op_sel_hi:[1,0,1]
	v_pk_fma_f32 v[52:53], v[98:99], v[108:109], v[52:53] op_sel:[0,1,0] op_sel_hi:[1,1,1]
	v_pk_mul_f32 v[164:165], v[38:39], v[100:101]
	v_pk_mul_f32 v[166:167], v[46:47], v[100:101]
	v_pk_fma_f32 v[164:165], v[40:41], v[102:103], v[164:165]
	v_pk_fma_f32 v[166:167], v[48:49], v[102:103], v[166:167]
	v_pk_fma_f32 v[164:165], v[42:43], v[104:105], v[164:165]
	v_pk_fma_f32 v[166:167], v[50:51], v[104:105], v[166:167]
	v_pk_fma_f32 v[164:165], v[44:45], v[106:107], v[164:165]
	v_pk_fma_f32 v[166:167], v[52:53], v[106:107], v[166:167]
	v_add_f32_e32 v164, v164, v165
	v_add_f32_e32 v166, v166, v167
	s_waitcnt lgkmcnt(0)
	ds_read_b128 v[68:71], v64 offset:7680
	v_add_f32_dpp v168, v164, v164 quad_perm:[1,0,3,2] row_mask:0xf bank_mask:0xf bound_ctrl:1
	v_add_f32_dpp v169, v166, v166 quad_perm:[1,0,3,2] row_mask:0xf bank_mask:0xf bound_ctrl:1
	ds_read_b128 v[72:75], v64 offset:7696
	v_add_f32_dpp v170, v168, v168 quad_perm:[2,3,0,1] row_mask:0xf bank_mask:0xf bound_ctrl:1
	v_add_f32_dpp v171, v169, v169 quad_perm:[2,3,0,1] row_mask:0xf bank_mask:0xf bound_ctrl:1
	ds_read_b128 v[76:79], v64 offset:7936
	v_add_f32_dpp v164, v170, v170 row_ror:8 row_mask:0xf bank_mask:0xf
	v_add_f32_dpp v166, v171, v171 row_ror:8 row_mask:0xf bank_mask:0xf
	ds_read_b128 v[80:83], v64 offset:7952
	ds_read_b128 v[84:87], v64 offset:8192
	ds_read_b128 v[88:91], v64 offset:8208
	ds_read_b128 v[92:95], v64 offset:8448
	ds_read_b128 v[96:99], v64 offset:8464
	ds_read_b128 v[100:103], v64 offset:8704
	ds_read_b128 v[104:107], v64 offset:8720
	ds_read2_b32 v[108:109], v67 offset0:0 offset1:2
	ds_write2_b32 v172, v164, v166 offset0:0 offset1:2
	v_pk_mul_f32 v[156:157], v[38:39], v[112:113]
	v_pk_mul_f32 v[158:159], v[46:47], v[112:113]
	v_pk_fma_f32 v[156:157], v[40:41], v[114:115], v[156:157]
	v_pk_fma_f32 v[158:159], v[48:49], v[114:115], v[158:159]
	v_pk_fma_f32 v[156:157], v[42:43], v[116:117], v[156:157]
	v_pk_fma_f32 v[158:159], v[50:51], v[116:117], v[158:159]
	v_pk_fma_f32 v[156:157], v[44:45], v[118:119], v[156:157]
	v_pk_fma_f32 v[158:159], v[52:53], v[118:119], v[158:159]
; __device__ __forceinline__ float red4(float x) { x += dppf(x, 0); x += dppf(x, 1); return x; }
; __device__ __forceinline__ void scan_phase(const Params& p, int j, unsigned char* smem) {
;     ...
;             for (int t = 0; t < 16; ++t) {
;                 const float* op = OPS + t * 320 + kq * 16;
;                 f32x4 A4[4], B4[4], W4[4], K4[4], R4[4];
; #pragma unroll
;                 for (int i = 0; i < 4; ++i) A4[i] = *(const f32x4*)(op + i * 4);
; #pragma unroll
;                 for (int i = 0; i < 4; ++i) { W4[i] = *(const f32x4*)(op + 128 + i * 4); B4[i] = *(const f32x4*)(op + 64 + i * 4); K4[i] = *(const f32x4*)(op + 192 + i * 4); }
; #pragma unroll
;                 for (int i = 0; i < 4; ++i) R4[i] = *(const f32x4*)(op + 256 + i * 4);
;                 const float vv = VB[t * 64 + vrow];
;                 f32x2 s0 = {0.f, 0.f}, s1 = {0.f, 0.f};
; #pragma unroll
;                 for (int i = 0; i < 4; ++i) { s0 += S[2 * i] * (f32x2){A4[i][0], A4[i][1]}; s1 += S[2 * i + 1] * (f32x2){A4[i][2], A4[i][3]}; }
;                 const float sa = red4((s0[0] + s0[1]) + (s1[0] + s1[1]));
;                 const f32x2 sa2 = {sa, sa}, vv2 = {vv, vv};
; #pragma unroll
;                 for (int i = 0; i < 4; ++i) {
;                     S[2 * i] = S[2 * i] * (f32x2){W4[i][0], W4[i][1]} + sa2 * (f32x2){B4[i][0], B4[i][1]} + vv2 * (f32x2){K4[i][0], K4[i][1]};
;                     S[2 * i + 1] = S[2 * i + 1] * (f32x2){W4[i][2], W4[i][3]} + sa2 * (f32x2){B4[i][2], B4[i][3]} + vv2 * (f32x2){K4[i][2], K4[i][3]};
;                 }
;                 f32x2 y0 = {0.f, 0.f}, y1 = {0.f, 0.f};
; #pragma unroll
;                 for (int i = 0; i < 4; ++i) { y0 += S[2 * i] * (f32x2){R4[i][0], R4[i][1]}; y1 += S[2 * i + 1] * (f32x2){R4[i][2], R4[i][3]}; }
;                 const float y = red4((y0[0] + y0[1]) + (y1[0] + y1[1]));
;                 if (kq == 0) YB[t * 64 + vrow] = y;
	v_add_f32_e32 v156, v156, v157
	v_add_f32_e32 v158, v158, v159
	v_pk_mul_f32 v[38:39], v[38:39], v[128:129]
	v_add_f32_dpp v168, v156, v156 quad_perm:[1,0,3,2] row_mask:0xf bank_mask:0xf bound_ctrl:1
	v_add_f32_dpp v169, v158, v158 quad_perm:[1,0,3,2] row_mask:0xf bank_mask:0xf bound_ctrl:1
	v_pk_mul_f32 v[46:47], v[46:47], v[128:129]
	v_add_f32_dpp v170, v168, v168 quad_perm:[2,3,0,1] row_mask:0xf bank_mask:0xf bound_ctrl:1
	v_add_f32_dpp v171, v169, v169 quad_perm:[2,3,0,1] row_mask:0xf bank_mask:0xf bound_ctrl:1
	v_pk_mul_f32 v[40:41], v[40:41], v[130:131]
	v_add_f32_dpp v160, v170, v170 row_ror:8 row_mask:0xf bank_mask:0xf
	v_add_f32_dpp v162, v171, v171 row_ror:8 row_mask:0xf bank_mask:0xf
	v_pk_mul_f32 v[48:49], v[48:49], v[130:131]
	v_pk_mul_f32 v[42:43], v[42:43], v[132:133]
	v_pk_mul_f32 v[50:51], v[50:51], v[132:133]
	v_pk_mul_f32 v[44:45], v[44:45], v[134:135]
	v_pk_mul_f32 v[52:53], v[52:53], v[134:135]
	v_pk_fma_f32 v[38:39], v[120:121], v[160:161], v[38:39] op_sel_hi:[1,0,1]
	v_pk_fma_f32 v[46:47], v[120:121], v[162:163], v[46:47] op_sel_hi:[1,0,1]
	v_pk_fma_f32 v[40:41], v[122:123], v[160:161], v[40:41] op_sel_hi:[1,0,1]
	v_pk_fma_f32 v[48:49], v[122:123], v[162:163], v[48:49] op_sel_hi:[1,0,1]
	v_pk_fma_f32 v[42:43], v[124:125], v[160:161], v[42:43] op_sel_hi:[1,0,1]
	v_pk_fma_f32 v[50:51], v[124:125], v[162:163], v[50:51] op_sel_hi:[1,0,1]
	v_pk_fma_f32 v[44:45], v[126:127], v[160:161], v[44:45] op_sel_hi:[1,0,1]
	v_pk_fma_f32 v[52:53], v[126:127], v[162:163], v[52:53] op_sel_hi:[1,0,1]
	v_pk_fma_f32 v[38:39], v[136:137], v[152:153], v[38:39] op_sel_hi:[1,0,1]
	v_pk_fma_f32 v[46:47], v[136:137], v[152:153], v[46:47] op_sel:[0,1,0] op_sel_hi:[1,1,1]
	v_pk_fma_f32 v[40:41], v[138:139], v[152:153], v[40:41] op_sel_hi:[1,0,1]
	v_pk_fma_f32 v[48:49], v[138:139], v[152:153], v[48:49] op_sel:[0,1,0] op_sel_hi:[1,1,1]
	v_pk_fma_f32 v[42:43], v[140:141], v[152:153], v[42:43] op_sel_hi:[1,0,1]
	v_pk_fma_f32 v[50:51], v[140:141], v[152:153], v[50:51] op_sel:[0,1,0] op_sel_hi:[1,1,1]
	v_pk_fma_f32 v[44:45], v[142:143], v[152:153], v[44:45] op_sel_hi:[1,0,1]
	v_pk_fma_f32 v[52:53], v[142:143], v[152:153], v[52:53] op_sel:[0,1,0] op_sel_hi:[1,1,1]
	v_pk_mul_f32 v[164:165], v[38:39], v[144:145]
	v_pk_mul_f32 v[166:167], v[46:47], v[144:145]
	v_pk_fma_f32 v[164:165], v[40:41], v[146:147], v[164:165]
	v_pk_fma_f32 v[166:167], v[48:49], v[146:147], v[166:167]
	v_pk_fma_f32 v[164:165], v[42:43], v[148:149], v[164:165]
	v_pk_fma_f32 v[166:167], v[50:51], v[148:149], v[166:167]
	v_pk_fma_f32 v[164:165], v[44:45], v[150:151], v[164:165]
	v_pk_fma_f32 v[166:167], v[52:53], v[150:151], v[166:167]
	v_add_f32_e32 v164, v164, v165
	v_add_f32_e32 v166, v166, v167
	s_waitcnt lgkmcnt(0)
	ds_read_b128 v[112:115], v64 offset:8960
	v_add_f32_dpp v168, v164, v164 quad_perm:[1,0,3,2] row_mask:0xf bank_mask:0xf bound_ctrl:1
	v_add_f32_dpp v169, v166, v166 quad_perm:[1,0,3,2] row_mask:0xf bank_mask:0xf bound_ctrl:1
	ds_read_b128 v[116:119], v64 offset:8976
	v_add_f32_dpp v170, v168, v168 quad_perm:[2,3,0,1] row_mask:0xf bank_mask:0xf bound_ctrl:1
	v_add_f32_dpp v171, v169, v169 quad_perm:[2,3,0,1] row_mask:0xf bank_mask:0xf bound_ctrl:1
	ds_read_b128 v[120:123], v64 offset:9216
	v_add_f32_dpp v164, v170, v170 row_ror:8 row_mask:0xf bank_mask:0xf
	v_add_f32_dpp v166, v171, v171 row_ror:8 row_mask:0xf bank_mask:0xf
	ds_read_b128 v[124:127], v64 offset:9232
	ds_read_b128 v[128:131], v64 offset:9472
	ds_read_b128 v[132:135], v64 offset:9488
	ds_read_b128 v[136:139], v64 offset:9728
	ds_read_b128 v[140:143], v64 offset:9744
	ds_read_b128 v[144:147], v64 offset:9984
	ds_read_b128 v[148:151], v64 offset:10000
	ds_read2_b32 v[152:153], v67 offset0:64 offset1:66
	ds_write2_b32 v172, v164, v166 offset0:64 offset1:66
	v_pk_mul_f32 v[156:157], v[38:39], v[68:69]
	v_pk_mul_f32 v[158:159], v[46:47], v[68:69]
	v_pk_fma_f32 v[156:157], v[40:41], v[70:71], v[156:157]
	v_pk_fma_f32 v[158:159], v[48:49], v[70:71], v[158:159]
	v_pk_fma_f32 v[156:157], v[42:43], v[72:73], v[156:157]
	v_pk_fma_f32 v[158:159], v[50:51], v[72:73], v[158:159]
	v_pk_fma_f32 v[156:157], v[44:45], v[74:75], v[156:157]
	v_pk_fma_f32 v[158:159], v[52:53], v[74:75], v[158:159]
	v_add_f32_e32 v156, v156, v157
	v_add_f32_e32 v158, v158, v159
	v_pk_mul_f32 v[38:39], v[38:39], v[84:85]
	v_add_f32_dpp v168, v156, v156 quad_perm:[1,0,3,2] row_mask:0xf bank_mask:0xf bound_ctrl:1
	v_add_f32_dpp v169, v158, v158 quad_perm:[1,0,3,2] row_mask:0xf bank_mask:0xf bound_ctrl:1
	v_pk_mul_f32 v[46:47], v[46:47], v[84:85]
	v_add_f32_dpp v170, v168, v168 quad_perm:[2,3,0,1] row_mask:0xf bank_mask:0xf bound_ctrl:1
	v_add_f32_dpp v171, v169, v169 quad_perm:[2,3,0,1] row_mask:0xf bank_mask:0xf bound_ctrl:1
	v_pk_mul_f32 v[40:41], v[40:41], v[86:87]
	v_add_f32_dpp v160, v170, v170 row_ror:8 row_mask:0xf bank_mask:0xf
	v_add_f32_dpp v162, v171, v171 row_ror:8 row_mask:0xf bank_mask:0xf
	v_pk_mul_f32 v[48:49], v[48:49], v[86:87]
	v_pk_mul_f32 v[42:43], v[42:43], v[88:89]
	v_pk_mul_f32 v[50:51], v[50:51], v[88:89]
	v_pk_mul_f32 v[44:45], v[44:45], v[90:91]
	v_pk_mul_f32 v[52:53], v[52:53], v[90:91]
	v_pk_fma_f32 v[38:39], v[76:77], v[160:161], v[38:39] op_sel_hi:[1,0,1]
	v_pk_fma_f32 v[46:47], v[76:77], v[162:163], v[46:47] op_sel_hi:[1,0,1]
	v_pk_fma_f32 v[40:41], v[78:79], v[160:161], v[40:41] op_sel_hi:[1,0,1]
	v_pk_fma_f32 v[48:49], v[78:79], v[162:163], v[48:49] op_sel_hi:[1,0,1]
	v_pk_fma_f32 v[42:43], v[80:81], v[160:161], v[42:43] op_sel_hi:[1,0,1]
	v_pk_fma_f32 v[50:51], v[80:81], v[162:163], v[50:51] op_sel_hi:[1,0,1]
	v_pk_fma_f32 v[44:45], v[82:83], v[160:161], v[44:45] op_sel_hi:[1,0,1]
	v_pk_fma_f32 v[52:53], v[82:83], v[162:163], v[52:53] op_sel_hi:[1,0,1]
	v_pk_fma_f32 v[38:39], v[92:93], v[108:109], v[38:39] op_sel_hi:[1,0,1]
	v_pk_fma_f32 v[46:47], v[92:93], v[108:109], v[46:47] op_sel:[0,1,0] op_sel_hi:[1,1,1]
	v_pk_fma_f32 v[40:41], v[94:95], v[108:109], v[40:41] op_sel_hi:[1,0,1]
	v_pk_fma_f32 v[48:49], v[94:95], v[108:109], v[48:49] op_sel:[0,1,0] op_sel_hi:[1,1,1]
	v_pk_fma_f32 v[42:43], v[96:97], v[108:109], v[42:43] op_sel_hi:[1,0,1]
	v_pk_fma_f32 v[50:51], v[96:97], v[108:109], v[50:51] op_sel:[0,1,0] op_sel_hi:[1,1,1]
	v_pk_fma_f32 v[44:45], v[98:99], v[108:109], v[44:45] op_sel_hi:[1,0,1]
	v_pk_fma_f32 v[52:53], v[98:99], v[108:109], v[52:53] op_sel:[0,1,0] op_sel_hi:[1,1,1]
	v_pk_mul_f32 v[164:165], v[38:39], v[100:101]
	v_pk_mul_f32 v[166:167], v[46:47], v[100:101]
	v_pk_fma_f32 v[164:165], v[40:41], v[102:103], v[164:165]
	v_pk_fma_f32 v[166:167], v[48:49], v[102:103], v[166:167]
	v_pk_fma_f32 v[164:165], v[42:43], v[104:105], v[164:165]
	v_pk_fma_f32 v[166:167], v[50:51], v[104:105], v[166:167]
	v_pk_fma_f32 v[164:165], v[44:45], v[106:107], v[164:165]
	v_pk_fma_f32 v[166:167], v[52:53], v[106:107], v[166:167]
	v_add_f32_e32 v164, v164, v165
	v_add_f32_e32 v166, v166, v167
	s_waitcnt lgkmcnt(0)
; __device__ __forceinline__ float red4(float x) { x += dppf(x, 0); x += dppf(x, 1); return x; }
; __device__ __forceinline__ void scan_phase(const Params& p, int j, unsigned char* smem) {
;     ...
;             for (int t = 0; t < 16; ++t) {
;                 const float* op = OPS + t * 320 + kq * 16;
;                 f32x4 A4[4], B4[4], W4[4], K4[4], R4[4];
; #pragma unroll
;                 for (int i = 0; i < 4; ++i) A4[i] = *(const f32x4*)(op + i * 4);
; #pragma unroll
;                 for (int i = 0; i < 4; ++i) { W4[i] = *(const f32x4*)(op + 128 + i * 4); B4[i] = *(const f32x4*)(op + 64 + i * 4); K4[i] = *(const f32x4*)(op + 192 + i * 4); }
; #pragma unroll
;                 for (int i = 0; i < 4; ++i) R4[i] = *(const f32x4*)(op + 256 + i * 4);
;                 const float vv = VB[t * 64 + vrow];
;                 f32x2 s0 = {0.f, 0.f}, s1 = {0.f, 0.f};
; #pragma unroll
;                 for (int i = 0; i < 4; ++i) { s0 += S[2 * i] * (f32x2){A4[i][0], A4[i][1]}; s1 += S[2 * i + 1] * (f32x2){A4[i][2], A4[i][3]}; }
;                 const float sa = red4((s0[0] + s0[1]) + (s1[0] + s1[1]));
;                 const f32x2 sa2 = {sa, sa}, vv2 = {vv, vv};
; #pragma unroll
;                 for (int i = 0; i < 4; ++i) {
;                     S[2 * i] = S[2 * i] * (f32x2){W4[i][0], W4[i][1]} + sa2 * (f32x2){B4[i][0], B4[i][1]} + vv2 * (f32x2){K4[i][0], K4[i][1]};
;                     S[2 * i + 1] = S[2 * i + 1] * (f32x2){W4[i][2], W4[i][3]} + sa2 * (f32x2){B4[i][2], B4[i][3]} + vv2 * (f32x2){K4[i][2], K4[i][3]};
;                 }
;                 f32x2 y0 = {0.f, 0.f}, y1 = {0.f, 0.f};
; #pragma unroll
;                 for (int i = 0; i < 4; ++i) { y0 += S[2 * i] * (f32x2){R4[i][0], R4[i][1]}; y1 += S[2 * i + 1] * (f32x2){R4[i][2], R4[i][3]}; }
;                 const float y = red4((y0[0] + y0[1]) + (y1[0] + y1[1]));
;                 if (kq == 0) YB[t * 64 + vrow] = y;
	ds_read_b128 v[68:71], v64 offset:10240
	v_add_f32_dpp v168, v164, v164 quad_perm:[1,0,3,2] row_mask:0xf bank_mask:0xf bound_ctrl:1
	v_add_f32_dpp v169, v166, v166 quad_perm:[1,0,3,2] row_mask:0xf bank_mask:0xf bound_ctrl:1
	ds_read_b128 v[72:75], v64 offset:10256
	v_add_f32_dpp v170, v168, v168 quad_perm:[2,3,0,1] row_mask:0xf bank_mask:0xf bound_ctrl:1
	v_add_f32_dpp v171, v169, v169 quad_perm:[2,3,0,1] row_mask:0xf bank_mask:0xf bound_ctrl:1
	ds_read_b128 v[76:79], v64 offset:10496
	v_add_f32_dpp v164, v170, v170 row_ror:8 row_mask:0xf bank_mask:0xf
	v_add_f32_dpp v166, v171, v171 row_ror:8 row_mask:0xf bank_mask:0xf
	ds_read_b128 v[80:83], v64 offset:10512
	ds_read_b128 v[84:87], v64 offset:10752
	ds_read_b128 v[88:91], v64 offset:10768
	ds_read_b128 v[92:95], v64 offset:11008
	ds_read_b128 v[96:99], v64 offset:11024
	ds_read_b128 v[100:103], v64 offset:11264
	ds_read_b128 v[104:107], v64 offset:11280
	ds_read2_b32 v[108:109], v67 offset0:128 offset1:130
	ds_write2_b32 v172, v164, v166 offset0:128 offset1:130
	v_pk_mul_f32 v[156:157], v[38:39], v[112:113]
	v_pk_mul_f32 v[158:159], v[46:47], v[112:113]
	v_pk_fma_f32 v[156:157], v[40:41], v[114:115], v[156:157]
	v_pk_fma_f32 v[158:159], v[48:49], v[114:115], v[158:159]
	v_pk_fma_f32 v[156:157], v[42:43], v[116:117], v[156:157]
	v_pk_fma_f32 v[158:159], v[50:51], v[116:117], v[158:159]
	v_pk_fma_f32 v[156:157], v[44:45], v[118:119], v[156:157]
	v_pk_fma_f32 v[158:159], v[52:53], v[118:119], v[158:159]
	v_add_f32_e32 v156, v156, v157
	v_add_f32_e32 v158, v158, v159
	v_pk_mul_f32 v[38:39], v[38:39], v[128:129]
	v_add_f32_dpp v168, v156, v156 quad_perm:[1,0,3,2] row_mask:0xf bank_mask:0xf bound_ctrl:1
	v_add_f32_dpp v169, v158, v158 quad_perm:[1,0,3,2] row_mask:0xf bank_mask:0xf bound_ctrl:1
	v_pk_mul_f32 v[46:47], v[46:47], v[128:129]
	v_add_f32_dpp v170, v168, v168 quad_perm:[2,3,0,1] row_mask:0xf bank_mask:0xf bound_ctrl:1
	v_add_f32_dpp v171, v169, v169 quad_perm:[2,3,0,1] row_mask:0xf bank_mask:0xf bound_ctrl:1
	v_pk_mul_f32 v[40:41], v[40:41], v[130:131]
	v_add_f32_dpp v160, v170, v170 row_ror:8 row_mask:0xf bank_mask:0xf
	v_add_f32_dpp v162, v171, v171 row_ror:8 row_mask:0xf bank_mask:0xf
	v_pk_mul_f32 v[48:49], v[48:49], v[130:131]
	v_pk_mul_f32 v[42:43], v[42:43], v[132:133]
	v_pk_mul_f32 v[50:51], v[50:51], v[132:133]
	v_pk_mul_f32 v[44:45], v[44:45], v[134:135]
	v_pk_mul_f32 v[52:53], v[52:53], v[134:135]
	v_pk_fma_f32 v[38:39], v[120:121], v[160:161], v[38:39] op_sel_hi:[1,0,1]
	v_pk_fma_f32 v[46:47], v[120:121], v[162:163], v[46:47] op_sel_hi:[1,0,1]
	v_pk_fma_f32 v[40:41], v[122:123], v[160:161], v[40:41] op_sel_hi:[1,0,1]
	v_pk_fma_f32 v[48:49], v[122:123], v[162:163], v[48:49] op_sel_hi:[1,0,1]
	v_pk_fma_f32 v[42:43], v[124:125], v[160:161], v[42:43] op_sel_hi:[1,0,1]
	v_pk_fma_f32 v[50:51], v[124:125], v[162:163], v[50:51] op_sel_hi:[1,0,1]
	v_pk_fma_f32 v[44:45], v[126:127], v[160:161], v[44:45] op_sel_hi:[1,0,1]
	v_pk_fma_f32 v[52:53], v[126:127], v[162:163], v[52:53] op_sel_hi:[1,0,1]
	v_pk_fma_f32 v[38:39], v[136:137], v[152:153], v[38:39] op_sel_hi:[1,0,1]
	v_pk_fma_f32 v[46:47], v[136:137], v[152:153], v[46:47] op_sel:[0,1,0] op_sel_hi:[1,1,1]
	v_pk_fma_f32 v[40:41], v[138:139], v[152:153], v[40:41] op_sel_hi:[1,0,1]
	v_pk_fma_f32 v[48:49], v[138:139], v[152:153], v[48:49] op_sel:[0,1,0] op_sel_hi:[1,1,1]
	v_pk_fma_f32 v[42:43], v[140:141], v[152:153], v[42:43] op_sel_hi:[1,0,1]
	v_pk_fma_f32 v[50:51], v[140:141], v[152:153], v[50:51] op_sel:[0,1,0] op_sel_hi:[1,1,1]
	v_pk_fma_f32 v[44:45], v[142:143], v[152:153], v[44:45] op_sel_hi:[1,0,1]
	v_pk_fma_f32 v[52:53], v[142:143], v[152:153], v[52:53] op_sel:[0,1,0] op_sel_hi:[1,1,1]
	v_pk_mul_f32 v[164:165], v[38:39], v[144:145]
	v_pk_mul_f32 v[166:167], v[46:47], v[144:145]
	v_pk_fma_f32 v[164:165], v[40:41], v[146:147], v[164:165]
	v_pk_fma_f32 v[166:167], v[48:49], v[146:147], v[166:167]
	v_pk_fma_f32 v[164:165], v[42:43], v[148:149], v[164:165]
	v_pk_fma_f32 v[166:167], v[50:51], v[148:149], v[166:167]
	v_pk_fma_f32 v[164:165], v[44:45], v[150:151], v[164:165]
	v_pk_fma_f32 v[166:167], v[52:53], v[150:151], v[166:167]
	v_add_f32_e32 v164, v164, v165
	v_add_f32_e32 v166, v166, v167
	s_waitcnt lgkmcnt(0)
	ds_read_b128 v[112:115], v64 offset:11520
	v_add_f32_dpp v168, v164, v164 quad_perm:[1,0,3,2] row_mask:0xf bank_mask:0xf bound_ctrl:1
	v_add_f32_dpp v169, v166, v166 quad_perm:[1,0,3,2] row_mask:0xf bank_mask:0xf bound_ctrl:1
	ds_read_b128 v[116:119], v64 offset:11536
	v_add_f32_dpp v170, v168, v168 quad_perm:[2,3,0,1] row_mask:0xf bank_mask:0xf bound_ctrl:1
	v_add_f32_dpp v171, v169, v169 quad_perm:[2,3,0,1] row_mask:0xf bank_mask:0xf bound_ctrl:1
	ds_read_b128 v[120:123], v64 offset:11776
	v_add_f32_dpp v164, v170, v170 row_ror:8 row_mask:0xf bank_mask:0xf
	v_add_f32_dpp v166, v171, v171 row_ror:8 row_mask:0xf bank_mask:0xf
	ds_read_b128 v[124:127], v64 offset:11792
	ds_read_b128 v[128:131], v64 offset:12032
	ds_read_b128 v[132:135], v64 offset:12048
	ds_read_b128 v[136:139], v64 offset:12288
	ds_read_b128 v[140:143], v64 offset:12304
	ds_read_b128 v[144:147], v64 offset:12544
	ds_read_b128 v[148:151], v64 offset:12560
	ds_read2_b32 v[152:153], v67 offset0:192 offset1:194
	ds_write2_b32 v172, v164, v166 offset0:192 offset1:194
	v_add_u32_e32 v67, 0x400, v67
	v_add_u32_e32 v172, 0x400, v172
	v_pk_mul_f32 v[156:157], v[38:39], v[68:69]
	v_pk_mul_f32 v[158:159], v[46:47], v[68:69]
	v_pk_fma_f32 v[156:157], v[40:41], v[70:71], v[156:157]
	v_pk_fma_f32 v[158:159], v[48:49], v[70:71], v[158:159]
	v_pk_fma_f32 v[156:157], v[42:43], v[72:73], v[156:157]
	v_pk_fma_f32 v[158:159], v[50:51], v[72:73], v[158:159]
; __device__ __forceinline__ float red4(float x) { x += dppf(x, 0); x += dppf(x, 1); return x; }
; __device__ __forceinline__ void scan_phase(const Params& p, int j, unsigned char* smem) {
;     ...
;             for (int t = 0; t < 16; ++t) {
;                 const float* op = OPS + t * 320 + kq * 16;
;                 f32x4 A4[4], B4[4], W4[4], K4[4], R4[4];
; #pragma unroll
;                 for (int i = 0; i < 4; ++i) A4[i] = *(const f32x4*)(op + i * 4);
; #pragma unroll
;                 for (int i = 0; i < 4; ++i) { W4[i] = *(const f32x4*)(op + 128 + i * 4); B4[i] = *(const f32x4*)(op + 64 + i * 4); K4[i] = *(const f32x4*)(op + 192 + i * 4); }
; #pragma unroll
;                 for (int i = 0; i < 4; ++i) R4[i] = *(const f32x4*)(op + 256 + i * 4);
;                 const float vv = VB[t * 64 + vrow];
;                 f32x2 s0 = {0.f, 0.f}, s1 = {0.f, 0.f};
; #pragma unroll
;                 for (int i = 0; i < 4; ++i) { s0 += S[2 * i] * (f32x2){A4[i][0], A4[i][1]}; s1 += S[2 * i + 1] * (f32x2){A4[i][2], A4[i][3]}; }
;                 const float sa = red4((s0[0] + s0[1]) + (s1[0] + s1[1]));
;                 const f32x2 sa2 = {sa, sa}, vv2 = {vv, vv};
; #pragma unroll
;                 for (int i = 0; i < 4; ++i) {
;                     S[2 * i] = S[2 * i] * (f32x2){W4[i][0], W4[i][1]} + sa2 * (f32x2){B4[i][0], B4[i][1]} + vv2 * (f32x2){K4[i][0], K4[i][1]};
;                     S[2 * i + 1] = S[2 * i + 1] * (f32x2){W4[i][2], W4[i][3]} + sa2 * (f32x2){B4[i][2], B4[i][3]} + vv2 * (f32x2){K4[i][2], K4[i][3]};
;                 }
;                 f32x2 y0 = {0.f, 0.f}, y1 = {0.f, 0.f};
; #pragma unroll
;                 for (int i = 0; i < 4; ++i) { y0 += S[2 * i] * (f32x2){R4[i][0], R4[i][1]}; y1 += S[2 * i + 1] * (f32x2){R4[i][2], R4[i][3]}; }
;                 const float y = red4((y0[0] + y0[1]) + (y1[0] + y1[1]));
;                 if (kq == 0) YB[t * 64 + vrow] = y;
	v_pk_fma_f32 v[156:157], v[44:45], v[74:75], v[156:157]
	v_pk_fma_f32 v[158:159], v[52:53], v[74:75], v[158:159]
	v_add_f32_e32 v156, v156, v157
	v_add_f32_e32 v158, v158, v159
	v_pk_mul_f32 v[38:39], v[38:39], v[84:85]
	v_add_f32_dpp v168, v156, v156 quad_perm:[1,0,3,2] row_mask:0xf bank_mask:0xf bound_ctrl:1
	v_add_f32_dpp v169, v158, v158 quad_perm:[1,0,3,2] row_mask:0xf bank_mask:0xf bound_ctrl:1
	v_pk_mul_f32 v[46:47], v[46:47], v[84:85]
	v_add_f32_dpp v170, v168, v168 quad_perm:[2,3,0,1] row_mask:0xf bank_mask:0xf bound_ctrl:1
	v_add_f32_dpp v171, v169, v169 quad_perm:[2,3,0,1] row_mask:0xf bank_mask:0xf bound_ctrl:1
	v_pk_mul_f32 v[40:41], v[40:41], v[86:87]
	v_add_f32_dpp v160, v170, v170 row_ror:8 row_mask:0xf bank_mask:0xf
	v_add_f32_dpp v162, v171, v171 row_ror:8 row_mask:0xf bank_mask:0xf
	v_pk_mul_f32 v[48:49], v[48:49], v[86:87]
	v_pk_mul_f32 v[42:43], v[42:43], v[88:89]
	v_pk_mul_f32 v[50:51], v[50:51], v[88:89]
	v_pk_mul_f32 v[44:45], v[44:45], v[90:91]
	v_pk_mul_f32 v[52:53], v[52:53], v[90:91]
	v_pk_fma_f32 v[38:39], v[76:77], v[160:161], v[38:39] op_sel_hi:[1,0,1]
	v_pk_fma_f32 v[46:47], v[76:77], v[162:163], v[46:47] op_sel_hi:[1,0,1]
	v_pk_fma_f32 v[40:41], v[78:79], v[160:161], v[40:41] op_sel_hi:[1,0,1]
	v_pk_fma_f32 v[48:49], v[78:79], v[162:163], v[48:49] op_sel_hi:[1,0,1]
	v_pk_fma_f32 v[42:43], v[80:81], v[160:161], v[42:43] op_sel_hi:[1,0,1]
	v_pk_fma_f32 v[50:51], v[80:81], v[162:163], v[50:51] op_sel_hi:[1,0,1]
	v_pk_fma_f32 v[44:45], v[82:83], v[160:161], v[44:45] op_sel_hi:[1,0,1]
	v_pk_fma_f32 v[52:53], v[82:83], v[162:163], v[52:53] op_sel_hi:[1,0,1]
	v_pk_fma_f32 v[38:39], v[92:93], v[108:109], v[38:39] op_sel_hi:[1,0,1]
	v_pk_fma_f32 v[46:47], v[92:93], v[108:109], v[46:47] op_sel:[0,1,0] op_sel_hi:[1,1,1]
	v_pk_fma_f32 v[40:41], v[94:95], v[108:109], v[40:41] op_sel_hi:[1,0,1]
	v_pk_fma_f32 v[48:49], v[94:95], v[108:109], v[48:49] op_sel:[0,1,0] op_sel_hi:[1,1,1]
	v_pk_fma_f32 v[42:43], v[96:97], v[108:109], v[42:43] op_sel_hi:[1,0,1]
	v_pk_fma_f32 v[50:51], v[96:97], v[108:109], v[50:51] op_sel:[0,1,0] op_sel_hi:[1,1,1]
	v_pk_fma_f32 v[44:45], v[98:99], v[108:109], v[44:45] op_sel_hi:[1,0,1]
	v_pk_fma_f32 v[52:53], v[98:99], v[108:109], v[52:53] op_sel:[0,1,0] op_sel_hi:[1,1,1]
	v_pk_mul_f32 v[164:165], v[38:39], v[100:101]
	v_pk_mul_f32 v[166:167], v[46:47], v[100:101]
	v_pk_fma_f32 v[164:165], v[40:41], v[102:103], v[164:165]
	v_pk_fma_f32 v[166:167], v[48:49], v[102:103], v[166:167]
	v_pk_fma_f32 v[164:165], v[42:43], v[104:105], v[164:165]
	v_pk_fma_f32 v[166:167], v[50:51], v[104:105], v[166:167]
	v_pk_fma_f32 v[164:165], v[44:45], v[106:107], v[164:165]
	v_pk_fma_f32 v[166:167], v[52:53], v[106:107], v[166:167]
	v_add_f32_e32 v164, v164, v165
	v_add_f32_e32 v166, v166, v167
	s_waitcnt lgkmcnt(0)
	ds_read_b128 v[68:71], v64 offset:12800
	v_add_f32_dpp v168, v164, v164 quad_perm:[1,0,3,2] row_mask:0xf bank_mask:0xf bound_ctrl:1
	v_add_f32_dpp v169, v166, v166 quad_perm:[1,0,3,2] row_mask:0xf bank_mask:0xf bound_ctrl:1
	ds_read_b128 v[72:75], v64 offset:12816
	v_add_f32_dpp v170, v168, v168 quad_perm:[2,3,0,1] row_mask:0xf bank_mask:0xf bound_ctrl:1
	v_add_f32_dpp v171, v169, v169 quad_perm:[2,3,0,1] row_mask:0xf bank_mask:0xf bound_ctrl:1
	ds_read_b128 v[76:79], v64 offset:13056
	v_add_f32_dpp v164, v170, v170 row_ror:8 row_mask:0xf bank_mask:0xf
	v_add_f32_dpp v166, v171, v171 row_ror:8 row_mask:0xf bank_mask:0xf
	ds_read_b128 v[80:83], v64 offset:13072
	ds_read_b128 v[84:87], v64 offset:13312
	ds_read_b128 v[88:91], v64 offset:13328
	ds_read_b128 v[92:95], v64 offset:13568
	ds_read_b128 v[96:99], v64 offset:13584
	ds_read_b128 v[100:103], v64 offset:13824
	ds_read_b128 v[104:107], v64 offset:13840
	ds_read2_b32 v[108:109], v67 offset0:0 offset1:2
	ds_write2_b32 v172, v164, v166 offset0:0 offset1:2
	v_pk_mul_f32 v[156:157], v[38:39], v[112:113]
	v_pk_mul_f32 v[158:159], v[46:47], v[112:113]
	v_pk_fma_f32 v[156:157], v[40:41], v[114:115], v[156:157]
	v_pk_fma_f32 v[158:159], v[48:49], v[114:115], v[158:159]
	v_pk_fma_f32 v[156:157], v[42:43], v[116:117], v[156:157]
	v_pk_fma_f32 v[158:159], v[50:51], v[116:117], v[158:159]
	v_pk_fma_f32 v[156:157], v[44:45], v[118:119], v[156:157]
	v_pk_fma_f32 v[158:159], v[52:53], v[118:119], v[158:159]
	v_add_f32_e32 v156, v156, v157
	v_add_f32_e32 v158, v158, v159
	v_pk_mul_f32 v[38:39], v[38:39], v[128:129]
	v_add_f32_dpp v168, v156, v156 quad_perm:[1,0,3,2] row_mask:0xf bank_mask:0xf bound_ctrl:1
	v_add_f32_dpp v169, v158, v158 quad_perm:[1,0,3,2] row_mask:0xf bank_mask:0xf bound_ctrl:1
	v_pk_mul_f32 v[46:47], v[46:47], v[128:129]
	v_add_f32_dpp v170, v168, v168 quad_perm:[2,3,0,1] row_mask:0xf bank_mask:0xf bound_ctrl:1
	v_add_f32_dpp v171, v169, v169 quad_perm:[2,3,0,1] row_mask:0xf bank_mask:0xf bound_ctrl:1
	v_pk_mul_f32 v[40:41], v[40:41], v[130:131]
	v_add_f32_dpp v160, v170, v170 row_ror:8 row_mask:0xf bank_mask:0xf
	v_add_f32_dpp v162, v171, v171 row_ror:8 row_mask:0xf bank_mask:0xf
	v_pk_mul_f32 v[48:49], v[48:49], v[130:131]
	v_pk_mul_f32 v[42:43], v[42:43], v[132:133]
	v_pk_mul_f32 v[50:51], v[50:51], v[132:133]
	v_pk_mul_f32 v[44:45], v[44:45], v[134:135]
	v_pk_mul_f32 v[52:53], v[52:53], v[134:135]
	v_pk_fma_f32 v[38:39], v[120:121], v[160:161], v[38:39] op_sel_hi:[1,0,1]
	v_pk_fma_f32 v[46:47], v[120:121], v[162:163], v[46:47] op_sel_hi:[1,0,1]
	v_pk_fma_f32 v[40:41], v[122:123], v[160:161], v[40:41] op_sel_hi:[1,0,1]
	v_pk_fma_f32 v[48:49], v[122:123], v[162:163], v[48:49] op_sel_hi:[1,0,1]
	v_pk_fma_f32 v[42:43], v[124:125], v[160:161], v[42:43] op_sel_hi:[1,0,1]
	v_pk_fma_f32 v[50:51], v[124:125], v[162:163], v[50:51] op_sel_hi:[1,0,1]
	v_pk_fma_f32 v[44:45], v[126:127], v[160:161], v[44:45] op_sel_hi:[1,0,1]
	v_pk_fma_f32 v[52:53], v[126:127], v[162:163], v[52:53] op_sel_hi:[1,0,1]
	v_pk_fma_f32 v[38:39], v[136:137], v[152:153], v[38:39] op_sel_hi:[1,0,1]
	v_pk_fma_f32 v[46:47], v[136:137], v[152:153], v[46:47] op_sel:[0,1,0] op_sel_hi:[1,1,1]
	v_pk_fma_f32 v[40:41], v[138:139], v[152:153], v[40:41] op_sel_hi:[1,0,1]
	v_pk_fma_f32 v[48:49], v[138:139], v[152:153], v[48:49] op_sel:[0,1,0] op_sel_hi:[1,1,1]
	v_pk_fma_f32 v[42:43], v[140:141], v[152:153], v[42:43] op_sel_hi:[1,0,1]
	v_pk_fma_f32 v[50:51], v[140:141], v[152:153], v[50:51] op_sel:[0,1,0] op_sel_hi:[1,1,1]
	v_pk_fma_f32 v[44:45], v[142:143], v[152:153], v[44:45] op_sel_hi:[1,0,1]
	v_pk_fma_f32 v[52:53], v[142:143], v[152:153], v[52:53] op_sel:[0,1,0] op_sel_hi:[1,1,1]
	v_pk_mul_f32 v[164:165], v[38:39], v[144:145]
	v_pk_mul_f32 v[166:167], v[46:47], v[144:145]
	v_pk_fma_f32 v[164:165], v[40:41], v[146:147], v[164:165]
	v_pk_fma_f32 v[166:167], v[48:49], v[146:147], v[166:167]
	v_pk_fma_f32 v[164:165], v[42:43], v[148:149], v[164:165]
	v_pk_fma_f32 v[166:167], v[50:51], v[148:149], v[166:167]
	v_pk_fma_f32 v[164:165], v[44:45], v[150:151], v[164:165]
	v_pk_fma_f32 v[166:167], v[52:53], v[150:151], v[166:167]
	v_add_f32_e32 v164, v164, v165
	v_add_f32_e32 v166, v166, v167
	s_waitcnt lgkmcnt(0)
; __device__ __forceinline__ float red4(float x) { x += dppf(x, 0); x += dppf(x, 1); return x; }
; __device__ __forceinline__ void scan_phase(const Params& p, int j, unsigned char* smem) {
;     ...
;             for (int t = 0; t < 16; ++t) {
;                 const float* op = OPS + t * 320 + kq * 16;
;                 f32x4 A4[4], B4[4], W4[4], K4[4], R4[4];
; #pragma unroll
;                 for (int i = 0; i < 4; ++i) A4[i] = *(const f32x4*)(op + i * 4);
; #pragma unroll
;                 for (int i = 0; i < 4; ++i) { W4[i] = *(const f32x4*)(op + 128 + i * 4); B4[i] = *(const f32x4*)(op + 64 + i * 4); K4[i] = *(const f32x4*)(op + 192 + i * 4); }
; #pragma unroll
;                 for (int i = 0; i < 4; ++i) R4[i] = *(const f32x4*)(op + 256 + i * 4);
;                 const float vv = VB[t * 64 + vrow];
;                 f32x2 s0 = {0.f, 0.f}, s1 = {0.f, 0.f};
; #pragma unroll
;                 for (int i = 0; i < 4; ++i) { s0 += S[2 * i] * (f32x2){A4[i][0], A4[i][1]}; s1 += S[2 * i + 1] * (f32x2){A4[i][2], A4[i][3]}; }
;                 const float sa = red4((s0[0] + s0[1]) + (s1[0] + s1[1]));
;                 const f32x2 sa2 = {sa, sa}, vv2 = {vv, vv};
; #pragma unroll
;                 for (int i = 0; i < 4; ++i) {
;                     S[2 * i] = S[2 * i] * (f32x2){W4[i][0], W4[i][1]} + sa2 * (f32x2){B4[i][0], B4[i][1]} + vv2 * (f32x2){K4[i][0], K4[i][1]};
;                     S[2 * i + 1] = S[2 * i + 1] * (f32x2){W4[i][2], W4[i][3]} + sa2 * (f32x2){B4[i][2], B4[i][3]} + vv2 * (f32x2){K4[i][2], K4[i][3]};
;                 }
;                 f32x2 y0 = {0.f, 0.f}, y1 = {0.f, 0.f};
; #pragma unroll
;                 for (int i = 0; i < 4; ++i) { y0 += S[2 * i] * (f32x2){R4[i][0], R4[i][1]}; y1 += S[2 * i + 1] * (f32x2){R4[i][2], R4[i][3]}; }
;                 const float y = red4((y0[0] + y0[1]) + (y1[0] + y1[1]));
;                 if (kq == 0) YB[t * 64 + vrow] = y;
	ds_read_b128 v[112:115], v64 offset:14080
	v_add_f32_dpp v168, v164, v164 quad_perm:[1,0,3,2] row_mask:0xf bank_mask:0xf bound_ctrl:1
	v_add_f32_dpp v169, v166, v166 quad_perm:[1,0,3,2] row_mask:0xf bank_mask:0xf bound_ctrl:1
	ds_read_b128 v[116:119], v64 offset:14096
	v_add_f32_dpp v170, v168, v168 quad_perm:[2,3,0,1] row_mask:0xf bank_mask:0xf bound_ctrl:1
	v_add_f32_dpp v171, v169, v169 quad_perm:[2,3,0,1] row_mask:0xf bank_mask:0xf bound_ctrl:1
	ds_read_b128 v[120:123], v64 offset:14336
	v_add_f32_dpp v164, v170, v170 row_ror:8 row_mask:0xf bank_mask:0xf
	v_add_f32_dpp v166, v171, v171 row_ror:8 row_mask:0xf bank_mask:0xf
	ds_read_b128 v[124:127], v64 offset:14352
	ds_read_b128 v[128:131], v64 offset:14592
	ds_read_b128 v[132:135], v64 offset:14608
	ds_read_b128 v[136:139], v64 offset:14848
	ds_read_b128 v[140:143], v64 offset:14864
	ds_read_b128 v[144:147], v64 offset:15104
	ds_read_b128 v[148:151], v64 offset:15120
	ds_read2_b32 v[152:153], v67 offset0:64 offset1:66
	ds_write2_b32 v172, v164, v166 offset0:64 offset1:66
	v_pk_mul_f32 v[156:157], v[38:39], v[68:69]
	v_pk_mul_f32 v[158:159], v[46:47], v[68:69]
	v_pk_fma_f32 v[156:157], v[40:41], v[70:71], v[156:157]
	v_pk_fma_f32 v[158:159], v[48:49], v[70:71], v[158:159]
	v_pk_fma_f32 v[156:157], v[42:43], v[72:73], v[156:157]
	v_pk_fma_f32 v[158:159], v[50:51], v[72:73], v[158:159]
	v_pk_fma_f32 v[156:157], v[44:45], v[74:75], v[156:157]
	v_pk_fma_f32 v[158:159], v[52:53], v[74:75], v[158:159]
	v_add_f32_e32 v156, v156, v157
	v_add_f32_e32 v158, v158, v159
	v_pk_mul_f32 v[38:39], v[38:39], v[84:85]
	v_add_f32_dpp v168, v156, v156 quad_perm:[1,0,3,2] row_mask:0xf bank_mask:0xf bound_ctrl:1
	v_add_f32_dpp v169, v158, v158 quad_perm:[1,0,3,2] row_mask:0xf bank_mask:0xf bound_ctrl:1
	v_pk_mul_f32 v[46:47], v[46:47], v[84:85]
	v_add_f32_dpp v170, v168, v168 quad_perm:[2,3,0,1] row_mask:0xf bank_mask:0xf bound_ctrl:1
	v_add_f32_dpp v171, v169, v169 quad_perm:[2,3,0,1] row_mask:0xf bank_mask:0xf bound_ctrl:1
	v_pk_mul_f32 v[40:41], v[40:41], v[86:87]
	v_add_f32_dpp v160, v170, v170 row_ror:8 row_mask:0xf bank_mask:0xf
	v_add_f32_dpp v162, v171, v171 row_ror:8 row_mask:0xf bank_mask:0xf
	v_pk_mul_f32 v[48:49], v[48:49], v[86:87]
	v_pk_mul_f32 v[42:43], v[42:43], v[88:89]
	v_pk_mul_f32 v[50:51], v[50:51], v[88:89]
	v_pk_mul_f32 v[44:45], v[44:45], v[90:91]
	v_pk_mul_f32 v[52:53], v[52:53], v[90:91]
	v_pk_fma_f32 v[38:39], v[76:77], v[160:161], v[38:39] op_sel_hi:[1,0,1]
	v_pk_fma_f32 v[46:47], v[76:77], v[162:163], v[46:47] op_sel_hi:[1,0,1]
	v_pk_fma_f32 v[40:41], v[78:79], v[160:161], v[40:41] op_sel_hi:[1,0,1]
	v_pk_fma_f32 v[48:49], v[78:79], v[162:163], v[48:49] op_sel_hi:[1,0,1]
	v_pk_fma_f32 v[42:43], v[80:81], v[160:161], v[42:43] op_sel_hi:[1,0,1]
	v_pk_fma_f32 v[50:51], v[80:81], v[162:163], v[50:51] op_sel_hi:[1,0,1]
	v_pk_fma_f32 v[44:45], v[82:83], v[160:161], v[44:45] op_sel_hi:[1,0,1]
	v_pk_fma_f32 v[52:53], v[82:83], v[162:163], v[52:53] op_sel_hi:[1,0,1]
	v_pk_fma_f32 v[38:39], v[92:93], v[108:109], v[38:39] op_sel_hi:[1,0,1]
	v_pk_fma_f32 v[46:47], v[92:93], v[108:109], v[46:47] op_sel:[0,1,0] op_sel_hi:[1,1,1]
	v_pk_fma_f32 v[40:41], v[94:95], v[108:109], v[40:41] op_sel_hi:[1,0,1]
	v_pk_fma_f32 v[48:49], v[94:95], v[108:109], v[48:49] op_sel:[0,1,0] op_sel_hi:[1,1,1]
	v_pk_fma_f32 v[42:43], v[96:97], v[108:109], v[42:43] op_sel_hi:[1,0,1]
	v_pk_fma_f32 v[50:51], v[96:97], v[108:109], v[50:51] op_sel:[0,1,0] op_sel_hi:[1,1,1]
	v_pk_fma_f32 v[44:45], v[98:99], v[108:109], v[44:45] op_sel_hi:[1,0,1]
	v_pk_fma_f32 v[52:53], v[98:99], v[108:109], v[52:53] op_sel:[0,1,0] op_sel_hi:[1,1,1]
	v_pk_mul_f32 v[164:165], v[38:39], v[100:101]
	v_pk_mul_f32 v[166:167], v[46:47], v[100:101]
	v_pk_fma_f32 v[164:165], v[40:41], v[102:103], v[164:165]
	v_pk_fma_f32 v[166:167], v[48:49], v[102:103], v[166:167]
	v_pk_fma_f32 v[164:165], v[42:43], v[104:105], v[164:165]
	v_pk_fma_f32 v[166:167], v[50:51], v[104:105], v[166:167]
	v_pk_fma_f32 v[164:165], v[44:45], v[106:107], v[164:165]
	v_pk_fma_f32 v[166:167], v[52:53], v[106:107], v[166:167]
	v_add_f32_e32 v164, v164, v165
	v_add_f32_e32 v166, v166, v167
	s_waitcnt lgkmcnt(0)
	ds_read_b128 v[68:71], v64 offset:15360
	v_add_f32_dpp v168, v164, v164 quad_perm:[1,0,3,2] row_mask:0xf bank_mask:0xf bound_ctrl:1
	v_add_f32_dpp v169, v166, v166 quad_perm:[1,0,3,2] row_mask:0xf bank_mask:0xf bound_ctrl:1
	ds_read_b128 v[72:75], v64 offset:15376
	v_add_f32_dpp v170, v168, v168 quad_perm:[2,3,0,1] row_mask:0xf bank_mask:0xf bound_ctrl:1
	v_add_f32_dpp v171, v169, v169 quad_perm:[2,3,0,1] row_mask:0xf bank_mask:0xf bound_ctrl:1
	ds_read_b128 v[76:79], v64 offset:15616
	v_add_f32_dpp v164, v170, v170 row_ror:8 row_mask:0xf bank_mask:0xf
	v_add_f32_dpp v166, v171, v171 row_ror:8 row_mask:0xf bank_mask:0xf
	ds_read_b128 v[80:83], v64 offset:15632
	ds_read_b128 v[84:87], v64 offset:15872
	ds_read_b128 v[88:91], v64 offset:15888
	ds_read_b128 v[92:95], v64 offset:16128
	ds_read_b128 v[96:99], v64 offset:16144
	ds_read_b128 v[100:103], v64 offset:16384
	ds_read_b128 v[104:107], v64 offset:16400
	ds_read2_b32 v[108:109], v67 offset0:128 offset1:130
	ds_write2_b32 v172, v164, v166 offset0:128 offset1:130
	v_pk_mul_f32 v[156:157], v[38:39], v[112:113]
	v_pk_mul_f32 v[158:159], v[46:47], v[112:113]
	v_pk_fma_f32 v[156:157], v[40:41], v[114:115], v[156:157]
	v_pk_fma_f32 v[158:159], v[48:49], v[114:115], v[158:159]
	v_pk_fma_f32 v[156:157], v[42:43], v[116:117], v[156:157]
	v_pk_fma_f32 v[158:159], v[50:51], v[116:117], v[158:159]
	v_pk_fma_f32 v[156:157], v[44:45], v[118:119], v[156:157]
	v_pk_fma_f32 v[158:159], v[52:53], v[118:119], v[158:159]
; __device__ __forceinline__ float red4(float x) { x += dppf(x, 0); x += dppf(x, 1); return x; }
; __device__ __forceinline__ void scan_phase(const Params& p, int j, unsigned char* smem) {
;     ...
;             for (int t = 0; t < 16; ++t) {
;                 const float* op = OPS + t * 320 + kq * 16;
;                 f32x4 A4[4], B4[4], W4[4], K4[4], R4[4];
; #pragma unroll
;                 for (int i = 0; i < 4; ++i) A4[i] = *(const f32x4*)(op + i * 4);
; #pragma unroll
;                 for (int i = 0; i < 4; ++i) { W4[i] = *(const f32x4*)(op + 128 + i * 4); B4[i] = *(const f32x4*)(op + 64 + i * 4); K4[i] = *(const f32x4*)(op + 192 + i * 4); }
; #pragma unroll
;                 for (int i = 0; i < 4; ++i) R4[i] = *(const f32x4*)(op + 256 + i * 4);
;                 const float vv = VB[t * 64 + vrow];
;                 f32x2 s0 = {0.f, 0.f}, s1 = {0.f, 0.f};
; #pragma unroll
;                 for (int i = 0; i < 4; ++i) { s0 += S[2 * i] * (f32x2){A4[i][0], A4[i][1]}; s1 += S[2 * i + 1] * (f32x2){A4[i][2], A4[i][3]}; }
;                 const float sa = red4((s0[0] + s0[1]) + (s1[0] + s1[1]));
;                 const f32x2 sa2 = {sa, sa}, vv2 = {vv, vv};
; #pragma unroll
;                 for (int i = 0; i < 4; ++i) {
;                     S[2 * i] = S[2 * i] * (f32x2){W4[i][0], W4[i][1]} + sa2 * (f32x2){B4[i][0], B4[i][1]} + vv2 * (f32x2){K4[i][0], K4[i][1]};
;                     S[2 * i + 1] = S[2 * i + 1] * (f32x2){W4[i][2], W4[i][3]} + sa2 * (f32x2){B4[i][2], B4[i][3]} + vv2 * (f32x2){K4[i][2], K4[i][3]};
;                 }
;                 f32x2 y0 = {0.f, 0.f}, y1 = {0.f, 0.f};
; #pragma unroll
;                 for (int i = 0; i < 4; ++i) { y0 += S[2 * i] * (f32x2){R4[i][0], R4[i][1]}; y1 += S[2 * i + 1] * (f32x2){R4[i][2], R4[i][3]}; }
;                 const float y = red4((y0[0] + y0[1]) + (y1[0] + y1[1]));
;                 if (kq == 0) YB[t * 64 + vrow] = y;
;             }
	v_add_f32_e32 v156, v156, v157
	v_add_f32_e32 v158, v158, v159
	v_pk_mul_f32 v[38:39], v[38:39], v[128:129]
	v_add_f32_dpp v168, v156, v156 quad_perm:[1,0,3,2] row_mask:0xf bank_mask:0xf bound_ctrl:1
	v_add_f32_dpp v169, v158, v158 quad_perm:[1,0,3,2] row_mask:0xf bank_mask:0xf bound_ctrl:1
	v_pk_mul_f32 v[46:47], v[46:47], v[128:129]
	v_add_f32_dpp v170, v168, v168 quad_perm:[2,3,0,1] row_mask:0xf bank_mask:0xf bound_ctrl:1
	v_add_f32_dpp v171, v169, v169 quad_perm:[2,3,0,1] row_mask:0xf bank_mask:0xf bound_ctrl:1
	v_pk_mul_f32 v[40:41], v[40:41], v[130:131]
	v_add_f32_dpp v160, v170, v170 row_ror:8 row_mask:0xf bank_mask:0xf
	v_add_f32_dpp v162, v171, v171 row_ror:8 row_mask:0xf bank_mask:0xf
	v_pk_mul_f32 v[48:49], v[48:49], v[130:131]
	v_pk_mul_f32 v[42:43], v[42:43], v[132:133]
	v_pk_mul_f32 v[50:51], v[50:51], v[132:133]
	v_pk_mul_f32 v[44:45], v[44:45], v[134:135]
	v_pk_mul_f32 v[52:53], v[52:53], v[134:135]
	v_pk_fma_f32 v[38:39], v[120:121], v[160:161], v[38:39] op_sel_hi:[1,0,1]
	v_pk_fma_f32 v[46:47], v[120:121], v[162:163], v[46:47] op_sel_hi:[1,0,1]
	v_pk_fma_f32 v[40:41], v[122:123], v[160:161], v[40:41] op_sel_hi:[1,0,1]
	v_pk_fma_f32 v[48:49], v[122:123], v[162:163], v[48:49] op_sel_hi:[1,0,1]
	v_pk_fma_f32 v[42:43], v[124:125], v[160:161], v[42:43] op_sel_hi:[1,0,1]
	v_pk_fma_f32 v[50:51], v[124:125], v[162:163], v[50:51] op_sel_hi:[1,0,1]
	v_pk_fma_f32 v[44:45], v[126:127], v[160:161], v[44:45] op_sel_hi:[1,0,1]
	v_pk_fma_f32 v[52:53], v[126:127], v[162:163], v[52:53] op_sel_hi:[1,0,1]
	v_pk_fma_f32 v[38:39], v[136:137], v[152:153], v[38:39] op_sel_hi:[1,0,1]
	v_pk_fma_f32 v[46:47], v[136:137], v[152:153], v[46:47] op_sel:[0,1,0] op_sel_hi:[1,1,1]
	v_pk_fma_f32 v[40:41], v[138:139], v[152:153], v[40:41] op_sel_hi:[1,0,1]
	v_pk_fma_f32 v[48:49], v[138:139], v[152:153], v[48:49] op_sel:[0,1,0] op_sel_hi:[1,1,1]
	v_pk_fma_f32 v[42:43], v[140:141], v[152:153], v[42:43] op_sel_hi:[1,0,1]
	v_pk_fma_f32 v[50:51], v[140:141], v[152:153], v[50:51] op_sel:[0,1,0] op_sel_hi:[1,1,1]
	v_pk_fma_f32 v[44:45], v[142:143], v[152:153], v[44:45] op_sel_hi:[1,0,1]
	v_pk_fma_f32 v[52:53], v[142:143], v[152:153], v[52:53] op_sel:[0,1,0] op_sel_hi:[1,1,1]
	v_pk_mul_f32 v[164:165], v[38:39], v[144:145]
	v_pk_mul_f32 v[166:167], v[46:47], v[144:145]
	v_pk_fma_f32 v[164:165], v[40:41], v[146:147], v[164:165]
	v_pk_fma_f32 v[166:167], v[48:49], v[146:147], v[166:167]
	v_pk_fma_f32 v[164:165], v[42:43], v[148:149], v[164:165]
	v_pk_fma_f32 v[166:167], v[50:51], v[148:149], v[166:167]
	v_pk_fma_f32 v[164:165], v[44:45], v[150:151], v[164:165]
	v_pk_fma_f32 v[166:167], v[52:53], v[150:151], v[166:167]
	v_add_f32_e32 v164, v164, v165
	v_add_f32_e32 v166, v166, v167
	s_waitcnt lgkmcnt(0)
	ds_read_b128 v[112:115], v64 offset:16640
	v_add_f32_dpp v168, v164, v164 quad_perm:[1,0,3,2] row_mask:0xf bank_mask:0xf bound_ctrl:1
	v_add_f32_dpp v169, v166, v166 quad_perm:[1,0,3,2] row_mask:0xf bank_mask:0xf bound_ctrl:1
	ds_read_b128 v[116:119], v64 offset:16656
	v_add_f32_dpp v170, v168, v168 quad_perm:[2,3,0,1] row_mask:0xf bank_mask:0xf bound_ctrl:1
	v_add_f32_dpp v171, v169, v169 quad_perm:[2,3,0,1] row_mask:0xf bank_mask:0xf bound_ctrl:1
	ds_read_b128 v[120:123], v64 offset:16896
	v_add_f32_dpp v164, v170, v170 row_ror:8 row_mask:0xf bank_mask:0xf
	v_add_f32_dpp v166, v171, v171 row_ror:8 row_mask:0xf bank_mask:0xf
	ds_read_b128 v[124:127], v64 offset:16912
	ds_read_b128 v[128:131], v64 offset:17152
	ds_read_b128 v[132:135], v64 offset:17168
	ds_read_b128 v[136:139], v64 offset:17408
	ds_read_b128 v[140:143], v64 offset:17424
	ds_read_b128 v[144:147], v64 offset:17664
	ds_read_b128 v[148:151], v64 offset:17680
	ds_read2_b32 v[152:153], v67 offset0:192 offset1:194
	ds_write2_b32 v172, v164, v166 offset0:192 offset1:194
	v_add_u32_e32 v67, 0x400, v67
	v_add_u32_e32 v172, 0x400, v172
	v_pk_mul_f32 v[156:157], v[38:39], v[68:69]
	v_pk_mul_f32 v[158:159], v[46:47], v[68:69]
	v_pk_fma_f32 v[156:157], v[40:41], v[70:71], v[156:157]
	v_pk_fma_f32 v[158:159], v[48:49], v[70:71], v[158:159]
	v_pk_fma_f32 v[156:157], v[42:43], v[72:73], v[156:157]
	v_pk_fma_f32 v[158:159], v[50:51], v[72:73], v[158:159]
	v_pk_fma_f32 v[156:157], v[44:45], v[74:75], v[156:157]
	v_pk_fma_f32 v[158:159], v[52:53], v[74:75], v[158:159]
	v_add_f32_e32 v156, v156, v157
	v_add_f32_e32 v158, v158, v159
	v_pk_mul_f32 v[38:39], v[38:39], v[84:85]
	v_add_f32_dpp v168, v156, v156 quad_perm:[1,0,3,2] row_mask:0xf bank_mask:0xf bound_ctrl:1
	v_add_f32_dpp v169, v158, v158 quad_perm:[1,0,3,2] row_mask:0xf bank_mask:0xf bound_ctrl:1
	v_pk_mul_f32 v[46:47], v[46:47], v[84:85]
	v_add_f32_dpp v170, v168, v168 quad_perm:[2,3,0,1] row_mask:0xf bank_mask:0xf bound_ctrl:1
	v_add_f32_dpp v171, v169, v169 quad_perm:[2,3,0,1] row_mask:0xf bank_mask:0xf bound_ctrl:1
	v_pk_mul_f32 v[40:41], v[40:41], v[86:87]
	v_add_f32_dpp v160, v170, v170 row_ror:8 row_mask:0xf bank_mask:0xf
	v_add_f32_dpp v162, v171, v171 row_ror:8 row_mask:0xf bank_mask:0xf
	v_pk_mul_f32 v[48:49], v[48:49], v[86:87]
	v_pk_mul_f32 v[42:43], v[42:43], v[88:89]
	v_pk_mul_f32 v[50:51], v[50:51], v[88:89]
	v_pk_mul_f32 v[44:45], v[44:45], v[90:91]
	v_pk_mul_f32 v[52:53], v[52:53], v[90:91]
	v_pk_fma_f32 v[38:39], v[76:77], v[160:161], v[38:39] op_sel_hi:[1,0,1]
	v_pk_fma_f32 v[46:47], v[76:77], v[162:163], v[46:47] op_sel_hi:[1,0,1]
	v_pk_fma_f32 v[40:41], v[78:79], v[160:161], v[40:41] op_sel_hi:[1,0,1]
	v_pk_fma_f32 v[48:49], v[78:79], v[162:163], v[48:49] op_sel_hi:[1,0,1]
	v_pk_fma_f32 v[42:43], v[80:81], v[160:161], v[42:43] op_sel_hi:[1,0,1]
	v_pk_fma_f32 v[50:51], v[80:81], v[162:163], v[50:51] op_sel_hi:[1,0,1]
	v_pk_fma_f32 v[44:45], v[82:83], v[160:161], v[44:45] op_sel_hi:[1,0,1]
	v_pk_fma_f32 v[52:53], v[82:83], v[162:163], v[52:53] op_sel_hi:[1,0,1]
	v_pk_fma_f32 v[38:39], v[92:93], v[108:109], v[38:39] op_sel_hi:[1,0,1]
	v_pk_fma_f32 v[46:47], v[92:93], v[108:109], v[46:47] op_sel:[0,1,0] op_sel_hi:[1,1,1]
	v_pk_fma_f32 v[40:41], v[94:95], v[108:109], v[40:41] op_sel_hi:[1,0,1]
	v_pk_fma_f32 v[48:49], v[94:95], v[108:109], v[48:49] op_sel:[0,1,0] op_sel_hi:[1,1,1]
	v_pk_fma_f32 v[42:43], v[96:97], v[108:109], v[42:43] op_sel_hi:[1,0,1]
	v_pk_fma_f32 v[50:51], v[96:97], v[108:109], v[50:51] op_sel:[0,1,0] op_sel_hi:[1,1,1]
	v_pk_fma_f32 v[44:45], v[98:99], v[108:109], v[44:45] op_sel_hi:[1,0,1]
	v_pk_fma_f32 v[52:53], v[98:99], v[108:109], v[52:53] op_sel:[0,1,0] op_sel_hi:[1,1,1]
	v_pk_mul_f32 v[164:165], v[38:39], v[100:101]
	v_pk_mul_f32 v[166:167], v[46:47], v[100:101]
	v_pk_fma_f32 v[164:165], v[40:41], v[102:103], v[164:165]
	v_pk_fma_f32 v[166:167], v[48:49], v[102:103], v[166:167]
	v_pk_fma_f32 v[164:165], v[42:43], v[104:105], v[164:165]
	v_pk_fma_f32 v[166:167], v[50:51], v[104:105], v[166:167]
	v_pk_fma_f32 v[164:165], v[44:45], v[106:107], v[164:165]
	v_pk_fma_f32 v[166:167], v[52:53], v[106:107], v[166:167]
	v_add_f32_e32 v164, v164, v165
	v_add_f32_e32 v166, v166, v167
	s_waitcnt lgkmcnt(0)
; __device__ __forceinline__ float red4(float x) { x += dppf(x, 0); x += dppf(x, 1); return x; }
; __device__ __forceinline__ void scan_phase(const Params& p, int j, unsigned char* smem) {
;     ...
;             for (int t = 0; t < 16; ++t) {
;                 const float* op = OPS + t * 320 + kq * 16;
;                 f32x4 A4[4], B4[4], W4[4], K4[4], R4[4];
; #pragma unroll
;                 for (int i = 0; i < 4; ++i) A4[i] = *(const f32x4*)(op + i * 4);
; #pragma unroll
;                 for (int i = 0; i < 4; ++i) { W4[i] = *(const f32x4*)(op + 128 + i * 4); B4[i] = *(const f32x4*)(op + 64 + i * 4); K4[i] = *(const f32x4*)(op + 192 + i * 4); }
; #pragma unroll
;                 for (int i = 0; i < 4; ++i) R4[i] = *(const f32x4*)(op + 256 + i * 4);
;                 const float vv = VB[t * 64 + vrow];
;                 f32x2 s0 = {0.f, 0.f}, s1 = {0.f, 0.f};
; #pragma unroll
;                 for (int i = 0; i < 4; ++i) { s0 += S[2 * i] * (f32x2){A4[i][0], A4[i][1]}; s1 += S[2 * i + 1] * (f32x2){A4[i][2], A4[i][3]}; }
;                 const float sa = red4((s0[0] + s0[1]) + (s1[0] + s1[1]));
;                 const f32x2 sa2 = {sa, sa}, vv2 = {vv, vv};
; #pragma unroll
;                 for (int i = 0; i < 4; ++i) {
;                     S[2 * i] = S[2 * i] * (f32x2){W4[i][0], W4[i][1]} + sa2 * (f32x2){B4[i][0], B4[i][1]} + vv2 * (f32x2){K4[i][0], K4[i][1]};
;                     S[2 * i + 1] = S[2 * i + 1] * (f32x2){W4[i][2], W4[i][3]} + sa2 * (f32x2){B4[i][2], B4[i][3]} + vv2 * (f32x2){K4[i][2], K4[i][3]};
;                 }
;                 f32x2 y0 = {0.f, 0.f}, y1 = {0.f, 0.f};
; #pragma unroll
;                 for (int i = 0; i < 4; ++i) { y0 += S[2 * i] * (f32x2){R4[i][0], R4[i][1]}; y1 += S[2 * i + 1] * (f32x2){R4[i][2], R4[i][3]}; }
;                 const float y = red4((y0[0] + y0[1]) + (y1[0] + y1[1]));
;                 if (kq == 0) YB[t * 64 + vrow] = y;
;             }
	ds_read_b128 v[68:71], v64 offset:17920
	v_add_f32_dpp v168, v164, v164 quad_perm:[1,0,3,2] row_mask:0xf bank_mask:0xf bound_ctrl:1
	v_add_f32_dpp v169, v166, v166 quad_perm:[1,0,3,2] row_mask:0xf bank_mask:0xf bound_ctrl:1
	ds_read_b128 v[72:75], v64 offset:17936
	v_add_f32_dpp v170, v168, v168 quad_perm:[2,3,0,1] row_mask:0xf bank_mask:0xf bound_ctrl:1
	v_add_f32_dpp v171, v169, v169 quad_perm:[2,3,0,1] row_mask:0xf bank_mask:0xf bound_ctrl:1
	ds_read_b128 v[76:79], v64 offset:18176
	v_add_f32_dpp v164, v170, v170 row_ror:8 row_mask:0xf bank_mask:0xf
	v_add_f32_dpp v166, v171, v171 row_ror:8 row_mask:0xf bank_mask:0xf
	ds_read_b128 v[80:83], v64 offset:18192
	ds_read_b128 v[84:87], v64 offset:18432
	ds_read_b128 v[88:91], v64 offset:18448
	ds_read_b128 v[92:95], v64 offset:18688
	ds_read_b128 v[96:99], v64 offset:18704
	ds_read_b128 v[100:103], v64 offset:18944
	ds_read_b128 v[104:107], v64 offset:18960
	ds_read2_b32 v[108:109], v67 offset0:0 offset1:2
	ds_write2_b32 v172, v164, v166 offset0:0 offset1:2
	v_pk_mul_f32 v[156:157], v[38:39], v[112:113]
	v_pk_mul_f32 v[158:159], v[46:47], v[112:113]
	v_pk_fma_f32 v[156:157], v[40:41], v[114:115], v[156:157]
	v_pk_fma_f32 v[158:159], v[48:49], v[114:115], v[158:159]
	v_pk_fma_f32 v[156:157], v[42:43], v[116:117], v[156:157]
	v_pk_fma_f32 v[158:159], v[50:51], v[116:117], v[158:159]
	v_pk_fma_f32 v[156:157], v[44:45], v[118:119], v[156:157]
	v_pk_fma_f32 v[158:159], v[52:53], v[118:119], v[158:159]
	v_add_f32_e32 v156, v156, v157
	v_add_f32_e32 v158, v158, v159
	v_pk_mul_f32 v[38:39], v[38:39], v[128:129]
	v_add_f32_dpp v168, v156, v156 quad_perm:[1,0,3,2] row_mask:0xf bank_mask:0xf bound_ctrl:1
	v_add_f32_dpp v169, v158, v158 quad_perm:[1,0,3,2] row_mask:0xf bank_mask:0xf bound_ctrl:1
	v_pk_mul_f32 v[46:47], v[46:47], v[128:129]
	v_add_f32_dpp v170, v168, v168 quad_perm:[2,3,0,1] row_mask:0xf bank_mask:0xf bound_ctrl:1
	v_add_f32_dpp v171, v169, v169 quad_perm:[2,3,0,1] row_mask:0xf bank_mask:0xf bound_ctrl:1
	v_pk_mul_f32 v[40:41], v[40:41], v[130:131]
	v_add_f32_dpp v160, v170, v170 row_ror:8 row_mask:0xf bank_mask:0xf
	v_add_f32_dpp v162, v171, v171 row_ror:8 row_mask:0xf bank_mask:0xf
	v_pk_mul_f32 v[48:49], v[48:49], v[130:131]
	v_pk_mul_f32 v[42:43], v[42:43], v[132:133]
	v_pk_mul_f32 v[50:51], v[50:51], v[132:133]
	v_pk_mul_f32 v[44:45], v[44:45], v[134:135]
	v_pk_mul_f32 v[52:53], v[52:53], v[134:135]
	v_pk_fma_f32 v[38:39], v[120:121], v[160:161], v[38:39] op_sel_hi:[1,0,1]
	v_pk_fma_f32 v[46:47], v[120:121], v[162:163], v[46:47] op_sel_hi:[1,0,1]
	v_pk_fma_f32 v[40:41], v[122:123], v[160:161], v[40:41] op_sel_hi:[1,0,1]
	v_pk_fma_f32 v[48:49], v[122:123], v[162:163], v[48:49] op_sel_hi:[1,0,1]
	v_pk_fma_f32 v[42:43], v[124:125], v[160:161], v[42:43] op_sel_hi:[1,0,1]
	v_pk_fma_f32 v[50:51], v[124:125], v[162:163], v[50:51] op_sel_hi:[1,0,1]
	v_pk_fma_f32 v[44:45], v[126:127], v[160:161], v[44:45] op_sel_hi:[1,0,1]
	v_pk_fma_f32 v[52:53], v[126:127], v[162:163], v[52:53] op_sel_hi:[1,0,1]
	v_pk_fma_f32 v[38:39], v[136:137], v[152:153], v[38:39] op_sel_hi:[1,0,1]
	v_pk_fma_f32 v[46:47], v[136:137], v[152:153], v[46:47] op_sel:[0,1,0] op_sel_hi:[1,1,1]
	v_pk_fma_f32 v[40:41], v[138:139], v[152:153], v[40:41] op_sel_hi:[1,0,1]
	v_pk_fma_f32 v[48:49], v[138:139], v[152:153], v[48:49] op_sel:[0,1,0] op_sel_hi:[1,1,1]
	v_pk_fma_f32 v[42:43], v[140:141], v[152:153], v[42:43] op_sel_hi:[1,0,1]
	v_pk_fma_f32 v[50:51], v[140:141], v[152:153], v[50:51] op_sel:[0,1,0] op_sel_hi:[1,1,1]
	v_pk_fma_f32 v[44:45], v[142:143], v[152:153], v[44:45] op_sel_hi:[1,0,1]
	v_pk_fma_f32 v[52:53], v[142:143], v[152:153], v[52:53] op_sel:[0,1,0] op_sel_hi:[1,1,1]
	v_pk_mul_f32 v[164:165], v[38:39], v[144:145]
	v_pk_mul_f32 v[166:167], v[46:47], v[144:145]
	v_pk_fma_f32 v[164:165], v[40:41], v[146:147], v[164:165]
	v_pk_fma_f32 v[166:167], v[48:49], v[146:147], v[166:167]
	v_pk_fma_f32 v[164:165], v[42:43], v[148:149], v[164:165]
	v_pk_fma_f32 v[166:167], v[50:51], v[148:149], v[166:167]
	v_pk_fma_f32 v[164:165], v[44:45], v[150:151], v[164:165]
	v_pk_fma_f32 v[166:167], v[52:53], v[150:151], v[166:167]
	v_add_f32_e32 v164, v164, v165
	v_add_f32_e32 v166, v166, v167
	s_waitcnt lgkmcnt(0)
	ds_read_b128 v[112:115], v64 offset:19200
	v_add_f32_dpp v168, v164, v164 quad_perm:[1,0,3,2] row_mask:0xf bank_mask:0xf bound_ctrl:1
	v_add_f32_dpp v169, v166, v166 quad_perm:[1,0,3,2] row_mask:0xf bank_mask:0xf bound_ctrl:1
	ds_read_b128 v[116:119], v64 offset:19216
	v_add_f32_dpp v170, v168, v168 quad_perm:[2,3,0,1] row_mask:0xf bank_mask:0xf bound_ctrl:1
	v_add_f32_dpp v171, v169, v169 quad_perm:[2,3,0,1] row_mask:0xf bank_mask:0xf bound_ctrl:1
	ds_read_b128 v[120:123], v64 offset:19456
	v_add_f32_dpp v164, v170, v170 row_ror:8 row_mask:0xf bank_mask:0xf
	v_add_f32_dpp v166, v171, v171 row_ror:8 row_mask:0xf bank_mask:0xf
	ds_read_b128 v[124:127], v64 offset:19472
	ds_read_b128 v[128:131], v64 offset:19712
	ds_read_b128 v[132:135], v64 offset:19728
	ds_read_b128 v[136:139], v64 offset:19968
	ds_read_b128 v[140:143], v64 offset:19984
	ds_read_b128 v[144:147], v64 offset:20224
	ds_read_b128 v[148:151], v64 offset:20240
	ds_read2_b32 v[152:153], v67 offset0:64 offset1:66
	ds_write2_b32 v172, v164, v166 offset0:64 offset1:66
	v_pk_mul_f32 v[156:157], v[38:39], v[68:69]
	v_pk_mul_f32 v[158:159], v[46:47], v[68:69]
	v_pk_fma_f32 v[156:157], v[40:41], v[70:71], v[156:157]
	v_pk_fma_f32 v[158:159], v[48:49], v[70:71], v[158:159]
	v_pk_fma_f32 v[156:157], v[42:43], v[72:73], v[156:157]
	v_pk_fma_f32 v[158:159], v[50:51], v[72:73], v[158:159]
	v_pk_fma_f32 v[156:157], v[44:45], v[74:75], v[156:157]
	v_pk_fma_f32 v[158:159], v[52:53], v[74:75], v[158:159]
; __device__ __forceinline__ float red4(float x) { x += dppf(x, 0); x += dppf(x, 1); return x; }
; __device__ __forceinline__ void scan_phase(const Params& p, int j, unsigned char* smem) {
;     ...
;             for (int t = 0; t < 16; ++t) {
;                 const float* op = OPS + t * 320 + kq * 16;
;                 f32x4 A4[4], B4[4], W4[4], K4[4], R4[4];
; #pragma unroll
;                 for (int i = 0; i < 4; ++i) A4[i] = *(const f32x4*)(op + i * 4);
; #pragma unroll
;                 for (int i = 0; i < 4; ++i) { W4[i] = *(const f32x4*)(op + 128 + i * 4); B4[i] = *(const f32x4*)(op + 64 + i * 4); K4[i] = *(const f32x4*)(op + 192 + i * 4); }
; #pragma unroll
;                 for (int i = 0; i < 4; ++i) R4[i] = *(const f32x4*)(op + 256 + i * 4);
;                 const float vv = VB[t * 64 + vrow];
;                 f32x2 s0 = {0.f, 0.f}, s1 = {0.f, 0.f};
; #pragma unroll
;                 for (int i = 0; i < 4; ++i) { s0 += S[2 * i] * (f32x2){A4[i][0], A4[i][1]}; s1 += S[2 * i + 1] * (f32x2){A4[i][2], A4[i][3]}; }
;                 const float sa = red4((s0[0] + s0[1]) + (s1[0] + s1[1]));
;                 const f32x2 sa2 = {sa, sa}, vv2 = {vv, vv};
; #pragma unroll
;                 for (int i = 0; i < 4; ++i) {
;                     S[2 * i] = S[2 * i] * (f32x2){W4[i][0], W4[i][1]} + sa2 * (f32x2){B4[i][0], B4[i][1]} + vv2 * (f32x2){K4[i][0], K4[i][1]};
;                     S[2 * i + 1] = S[2 * i + 1] * (f32x2){W4[i][2], W4[i][3]} + sa2 * (f32x2){B4[i][2], B4[i][3]} + vv2 * (f32x2){K4[i][2], K4[i][3]};
;                 }
;                 f32x2 y0 = {0.f, 0.f}, y1 = {0.f, 0.f};
; #pragma unroll
;                 for (int i = 0; i < 4; ++i) { y0 += S[2 * i] * (f32x2){R4[i][0], R4[i][1]}; y1 += S[2 * i + 1] * (f32x2){R4[i][2], R4[i][3]}; }
;                 const float y = red4((y0[0] + y0[1]) + (y1[0] + y1[1]));
;                 if (kq == 0) YB[t * 64 + vrow] = y;
;             }
	v_add_f32_e32 v156, v156, v157
	v_add_f32_e32 v158, v158, v159
	v_pk_mul_f32 v[38:39], v[38:39], v[84:85]
	v_add_f32_dpp v168, v156, v156 quad_perm:[1,0,3,2] row_mask:0xf bank_mask:0xf bound_ctrl:1
	v_add_f32_dpp v169, v158, v158 quad_perm:[1,0,3,2] row_mask:0xf bank_mask:0xf bound_ctrl:1
	v_pk_mul_f32 v[46:47], v[46:47], v[84:85]
	v_add_f32_dpp v170, v168, v168 quad_perm:[2,3,0,1] row_mask:0xf bank_mask:0xf bound_ctrl:1
	v_add_f32_dpp v171, v169, v169 quad_perm:[2,3,0,1] row_mask:0xf bank_mask:0xf bound_ctrl:1
	v_pk_mul_f32 v[40:41], v[40:41], v[86:87]
	v_add_f32_dpp v160, v170, v170 row_ror:8 row_mask:0xf bank_mask:0xf
	v_add_f32_dpp v162, v171, v171 row_ror:8 row_mask:0xf bank_mask:0xf
	v_pk_mul_f32 v[48:49], v[48:49], v[86:87]
	v_pk_mul_f32 v[42:43], v[42:43], v[88:89]
	v_pk_mul_f32 v[50:51], v[50:51], v[88:89]
	v_pk_mul_f32 v[44:45], v[44:45], v[90:91]
	v_pk_mul_f32 v[52:53], v[52:53], v[90:91]
	v_pk_fma_f32 v[38:39], v[76:77], v[160:161], v[38:39] op_sel_hi:[1,0,1]
	v_pk_fma_f32 v[46:47], v[76:77], v[162:163], v[46:47] op_sel_hi:[1,0,1]
	v_pk_fma_f32 v[40:41], v[78:79], v[160:161], v[40:41] op_sel_hi:[1,0,1]
	v_pk_fma_f32 v[48:49], v[78:79], v[162:163], v[48:49] op_sel_hi:[1,0,1]
	v_pk_fma_f32 v[42:43], v[80:81], v[160:161], v[42:43] op_sel_hi:[1,0,1]
	v_pk_fma_f32 v[50:51], v[80:81], v[162:163], v[50:51] op_sel_hi:[1,0,1]
	v_pk_fma_f32 v[44:45], v[82:83], v[160:161], v[44:45] op_sel_hi:[1,0,1]
	v_pk_fma_f32 v[52:53], v[82:83], v[162:163], v[52:53] op_sel_hi:[1,0,1]
	v_pk_fma_f32 v[38:39], v[92:93], v[108:109], v[38:39] op_sel_hi:[1,0,1]
	v_pk_fma_f32 v[46:47], v[92:93], v[108:109], v[46:47] op_sel:[0,1,0] op_sel_hi:[1,1,1]
	v_pk_fma_f32 v[40:41], v[94:95], v[108:109], v[40:41] op_sel_hi:[1,0,1]
	v_pk_fma_f32 v[48:49], v[94:95], v[108:109], v[48:49] op_sel:[0,1,0] op_sel_hi:[1,1,1]
	v_pk_fma_f32 v[42:43], v[96:97], v[108:109], v[42:43] op_sel_hi:[1,0,1]
	v_pk_fma_f32 v[50:51], v[96:97], v[108:109], v[50:51] op_sel:[0,1,0] op_sel_hi:[1,1,1]
	v_pk_fma_f32 v[44:45], v[98:99], v[108:109], v[44:45] op_sel_hi:[1,0,1]
	v_pk_fma_f32 v[52:53], v[98:99], v[108:109], v[52:53] op_sel:[0,1,0] op_sel_hi:[1,1,1]
	v_pk_mul_f32 v[164:165], v[38:39], v[100:101]
	v_pk_mul_f32 v[166:167], v[46:47], v[100:101]
	v_pk_fma_f32 v[164:165], v[40:41], v[102:103], v[164:165]
	v_pk_fma_f32 v[166:167], v[48:49], v[102:103], v[166:167]
	v_pk_fma_f32 v[164:165], v[42:43], v[104:105], v[164:165]
	v_pk_fma_f32 v[166:167], v[50:51], v[104:105], v[166:167]
	v_pk_fma_f32 v[164:165], v[44:45], v[106:107], v[164:165]
	v_pk_fma_f32 v[166:167], v[52:53], v[106:107], v[166:167]
	v_add_f32_e32 v164, v164, v165
	v_add_f32_e32 v166, v166, v167
	s_waitcnt lgkmcnt(0)
; __device__ __forceinline__ float red4(float x) { x += dppf(x, 0); x += dppf(x, 1); return x; }
; __device__ __forceinline__ void scan_phase(const Params& p, int j, unsigned char* smem) {
;     ...
;             for (int t = 0; t < 16; ++t) {
;                 const float* op = OPS + t * 320 + kq * 16;
;                 f32x4 A4[4], B4[4], W4[4], K4[4], R4[4];
; #pragma unroll
;                 for (int i = 0; i < 4; ++i) A4[i] = *(const f32x4*)(op + i * 4);
; #pragma unroll
;                 for (int i = 0; i < 4; ++i) { W4[i] = *(const f32x4*)(op + 128 + i * 4); B4[i] = *(const f32x4*)(op + 64 + i * 4); K4[i] = *(const f32x4*)(op + 192 + i * 4); }
; #pragma unroll
;                 for (int i = 0; i < 4; ++i) R4[i] = *(const f32x4*)(op + 256 + i * 4);
;                 const float vv = VB[t * 64 + vrow];
;                 f32x2 s0 = {0.f, 0.f}, s1 = {0.f, 0.f};
; #pragma unroll
;                 for (int i = 0; i < 4; ++i) { s0 += S[2 * i] * (f32x2){A4[i][0], A4[i][1]}; s1 += S[2 * i + 1] * (f32x2){A4[i][2], A4[i][3]}; }
;                 const float sa = red4((s0[0] + s0[1]) + (s1[0] + s1[1]));
;                 const f32x2 sa2 = {sa, sa}, vv2 = {vv, vv};
; #pragma unroll
;                 for (int i = 0; i < 4; ++i) {
;                     S[2 * i] = S[2 * i] * (f32x2){W4[i][0], W4[i][1]} + sa2 * (f32x2){B4[i][0], B4[i][1]} + vv2 * (f32x2){K4[i][0], K4[i][1]};
;                     S[2 * i + 1] = S[2 * i + 1] * (f32x2){W4[i][2], W4[i][3]} + sa2 * (f32x2){B4[i][2], B4[i][3]} + vv2 * (f32x2){K4[i][2], K4[i][3]};
;                 }
;                 f32x2 y0 = {0.f, 0.f}, y1 = {0.f, 0.f};
; #pragma unroll
;                 for (int i = 0; i < 4; ++i) { y0 += S[2 * i] * (f32x2){R4[i][0], R4[i][1]}; y1 += S[2 * i + 1] * (f32x2){R4[i][2], R4[i][3]}; }
;                 const float y = red4((y0[0] + y0[1]) + (y1[0] + y1[1]));
;                 if (kq == 0) YB[t * 64 + vrow] = y;
;             }
	ds_read_b128 v[68:71], v64 offset:20480
	v_add_f32_dpp v168, v164, v164 quad_perm:[1,0,3,2] row_mask:0xf bank_mask:0xf bound_ctrl:1
	v_add_f32_dpp v169, v166, v166 quad_perm:[1,0,3,2] row_mask:0xf bank_mask:0xf bound_ctrl:1
	ds_read_b128 v[72:75], v64 offset:20496
	v_add_f32_dpp v170, v168, v168 quad_perm:[2,3,0,1] row_mask:0xf bank_mask:0xf bound_ctrl:1
	v_add_f32_dpp v171, v169, v169 quad_perm:[2,3,0,1] row_mask:0xf bank_mask:0xf bound_ctrl:1
	ds_read_b128 v[76:79], v64 offset:20736
	v_add_f32_dpp v164, v170, v170 row_ror:8 row_mask:0xf bank_mask:0xf
	v_add_f32_dpp v166, v171, v171 row_ror:8 row_mask:0xf bank_mask:0xf
	ds_read_b128 v[80:83], v64 offset:20752
	ds_read_b128 v[84:87], v64 offset:20992
	ds_read_b128 v[88:91], v64 offset:21008
	ds_read_b128 v[92:95], v64 offset:21248
	ds_read_b128 v[96:99], v64 offset:21264
	ds_read_b128 v[100:103], v64 offset:21504
	ds_read_b128 v[104:107], v64 offset:21520
	ds_read2_b32 v[108:109], v67 offset0:128 offset1:130
	ds_write2_b32 v172, v164, v166 offset0:128 offset1:130
	v_pk_mul_f32 v[156:157], v[38:39], v[112:113]
	v_pk_mul_f32 v[158:159], v[46:47], v[112:113]
	v_pk_fma_f32 v[156:157], v[40:41], v[114:115], v[156:157]
	v_pk_fma_f32 v[158:159], v[48:49], v[114:115], v[158:159]
	v_pk_fma_f32 v[156:157], v[42:43], v[116:117], v[156:157]
	v_pk_fma_f32 v[158:159], v[50:51], v[116:117], v[158:159]
	v_pk_fma_f32 v[156:157], v[44:45], v[118:119], v[156:157]
	v_pk_fma_f32 v[158:159], v[52:53], v[118:119], v[158:159]
	v_add_f32_e32 v156, v156, v157
	v_add_f32_e32 v158, v158, v159
	v_pk_mul_f32 v[38:39], v[38:39], v[128:129]
	v_add_f32_dpp v168, v156, v156 quad_perm:[1,0,3,2] row_mask:0xf bank_mask:0xf bound_ctrl:1
	v_add_f32_dpp v169, v158, v158 quad_perm:[1,0,3,2] row_mask:0xf bank_mask:0xf bound_ctrl:1
	v_pk_mul_f32 v[46:47], v[46:47], v[128:129]
	v_add_f32_dpp v170, v168, v168 quad_perm:[2,3,0,1] row_mask:0xf bank_mask:0xf bound_ctrl:1
	v_add_f32_dpp v171, v169, v169 quad_perm:[2,3,0,1] row_mask:0xf bank_mask:0xf bound_ctrl:1
	v_pk_mul_f32 v[40:41], v[40:41], v[130:131]
	v_add_f32_dpp v160, v170, v170 row_ror:8 row_mask:0xf bank_mask:0xf
	v_add_f32_dpp v162, v171, v171 row_ror:8 row_mask:0xf bank_mask:0xf
	v_pk_mul_f32 v[48:49], v[48:49], v[130:131]
	v_pk_mul_f32 v[42:43], v[42:43], v[132:133]
	v_pk_mul_f32 v[50:51], v[50:51], v[132:133]
	v_pk_mul_f32 v[44:45], v[44:45], v[134:135]
	v_pk_mul_f32 v[52:53], v[52:53], v[134:135]
	v_pk_fma_f32 v[38:39], v[120:121], v[160:161], v[38:39] op_sel_hi:[1,0,1]
	v_pk_fma_f32 v[46:47], v[120:121], v[162:163], v[46:47] op_sel_hi:[1,0,1]
	v_pk_fma_f32 v[40:41], v[122:123], v[160:161], v[40:41] op_sel_hi:[1,0,1]
	v_pk_fma_f32 v[48:49], v[122:123], v[162:163], v[48:49] op_sel_hi:[1,0,1]
	v_pk_fma_f32 v[42:43], v[124:125], v[160:161], v[42:43] op_sel_hi:[1,0,1]
	v_pk_fma_f32 v[50:51], v[124:125], v[162:163], v[50:51] op_sel_hi:[1,0,1]
	v_pk_fma_f32 v[44:45], v[126:127], v[160:161], v[44:45] op_sel_hi:[1,0,1]
	v_pk_fma_f32 v[52:53], v[126:127], v[162:163], v[52:53] op_sel_hi:[1,0,1]
	v_pk_fma_f32 v[38:39], v[136:137], v[152:153], v[38:39] op_sel_hi:[1,0,1]
	v_pk_fma_f32 v[46:47], v[136:137], v[152:153], v[46:47] op_sel:[0,1,0] op_sel_hi:[1,1,1]
	v_pk_fma_f32 v[40:41], v[138:139], v[152:153], v[40:41] op_sel_hi:[1,0,1]
	v_pk_fma_f32 v[48:49], v[138:139], v[152:153], v[48:49] op_sel:[0,1,0] op_sel_hi:[1,1,1]
	v_pk_fma_f32 v[42:43], v[140:141], v[152:153], v[42:43] op_sel_hi:[1,0,1]
	v_pk_fma_f32 v[50:51], v[140:141], v[152:153], v[50:51] op_sel:[0,1,0] op_sel_hi:[1,1,1]
	v_pk_fma_f32 v[44:45], v[142:143], v[152:153], v[44:45] op_sel_hi:[1,0,1]
	v_pk_fma_f32 v[52:53], v[142:143], v[152:153], v[52:53] op_sel:[0,1,0] op_sel_hi:[1,1,1]
	v_pk_mul_f32 v[164:165], v[38:39], v[144:145]
	v_pk_mul_f32 v[166:167], v[46:47], v[144:145]
	v_pk_fma_f32 v[164:165], v[40:41], v[146:147], v[164:165]
	v_pk_fma_f32 v[166:167], v[48:49], v[146:147], v[166:167]
	v_pk_fma_f32 v[164:165], v[42:43], v[148:149], v[164:165]
	v_pk_fma_f32 v[166:167], v[50:51], v[148:149], v[166:167]
	v_pk_fma_f32 v[164:165], v[44:45], v[150:151], v[164:165]
	v_pk_fma_f32 v[166:167], v[52:53], v[150:151], v[166:167]
	v_add_f32_e32 v164, v164, v165
	v_add_f32_e32 v166, v166, v167
	s_waitcnt lgkmcnt(0)
	ds_read_b128 v[112:115], v64 offset:21760
	v_add_f32_dpp v168, v164, v164 quad_perm:[1,0,3,2] row_mask:0xf bank_mask:0xf bound_ctrl:1
	v_add_f32_dpp v169, v166, v166 quad_perm:[1,0,3,2] row_mask:0xf bank_mask:0xf bound_ctrl:1
	ds_read_b128 v[116:119], v64 offset:21776
	v_add_f32_dpp v170, v168, v168 quad_perm:[2,3,0,1] row_mask:0xf bank_mask:0xf bound_ctrl:1
	v_add_f32_dpp v171, v169, v169 quad_perm:[2,3,0,1] row_mask:0xf bank_mask:0xf bound_ctrl:1
	ds_read_b128 v[120:123], v64 offset:22016
	v_add_f32_dpp v164, v170, v170 row_ror:8 row_mask:0xf bank_mask:0xf
	v_add_f32_dpp v166, v171, v171 row_ror:8 row_mask:0xf bank_mask:0xf
	ds_read_b128 v[124:127], v64 offset:22032
	ds_read_b128 v[128:131], v64 offset:22272
	ds_read_b128 v[132:135], v64 offset:22288
	ds_read_b128 v[136:139], v64 offset:22528
	ds_read_b128 v[140:143], v64 offset:22544
	ds_read_b128 v[144:147], v64 offset:22784
	ds_read_b128 v[148:151], v64 offset:22800
	ds_read2_b32 v[152:153], v67 offset0:192 offset1:194
	ds_write2_b32 v172, v164, v166 offset0:192 offset1:194
	s_branch .LBB0_504
